# GEMM K-loops: both priority flips hidden (raise after the last DMA, lower before the last MFMA), vmcnt+lgkmcnt waits merged into one instruction
# baseline (speedup 1.0000x reference)
; #define PG8_STAGE(bufoff, gbase, voff) do { _Pragma("unroll") for (int _i = 0; _i < 2; ++_i) \
;         __builtin_amdgcn_global_load_lds((const unsigned*)((const char*)(gbase) + (voff)[_i]), (LAS unsigned*)(lds + (bufoff) + ldsw + _i * 8192), 16, 0, 0); } while (0)
; #define PG8_LDA(dst, b, h) do { _Pragma("unroll") for (int m = 0; m < 4; ++m) _Pragma("unroll") for (int k = 0; k < 2; ++k) dst[m][k] = *(const LAS bf16x8*)(lds + PG8_SA(b, h) + aoff + m * 2048 + k * 1024); } while (0)
; #define PG8_LDB(dst, b, h) do { _Pragma("unroll") for (int n = 0; n < 2; ++n) _Pragma("unroll") for (int k = 0; k < 2; ++k) dst[n][k] = *(const LAS bf16x8*)(lds + PG8_SB(b, h) + boff + n * 2048 + k * 1024); } while (0)
; #define PG8_MMA(ai, bj, At, Bt) do { __builtin_amdgcn_s_setprio(1); _Pragma("unroll") for (int m = 0; m < 4; ++m) _Pragma("unroll") for (int n = 0; n < 2; ++n) _Pragma("unroll") for (int k = 0; k < 2; ++k) \
;         acc[ai][bj][m][n] = __builtin_amdgcn_mfma_f32_16x16x32_bf16(Bt[n][k], At[m][k], acc[ai][bj][m][n], 0, 0, 0); __builtin_amdgcn_s_setprio(0); } while (0)
; #define PG8_WAIT_V(n) asm volatile("s_waitcnt vmcnt(" #n ")" ::: "memory")
; #define PG8_BAR __builtin_amdgcn_s_barrier()
; template <class Epi, bool SEG>
; __device__ __forceinline__ void gemm_phase(LAS unsigned char* lds, const Gemm g, const int G, const int cidx, const Epi& E) {
;     ...
;             PG8_LDB(B0, 0, 0); PG8_LDB(B1, 0, 1); PG8_SCHED; PG8_LDA(At, 0, 0); PG8_STAGE(PG8_SA(1, 1), a1 + hstepA, voffA);
;             PG8_WAIT_V(8); PG8_WAIT_L(0); PG8_BAR; PG8_MMA(0, 0, At, B0); PG8_MMA(0, 1, At, B1); PG8_BAR; PG8_SCHED;
;             PG8_LDA(At, 0, 1); PG8_STAGE(PG8_SB(0, 0), b2, voffB); PG8_STAGE(PG8_SB(0, 1), b2 + hstepB, voffB); PG8_STAGE(PG8_SA(0, 0), a2, voffA);
;             PG8_WAIT_V(8); PG8_WAIT_L(0); PG8_BAR; PG8_MMA(1, 0, At, B0); PG8_MMA(1, 1, At, B1); PG8_BAR; PG8_SCHED;
;             PG8_LDB(B0, 1, 0); PG8_LDB(B1, 1, 1); PG8_SCHED; PG8_LDA(At, 1, 0); PG8_STAGE(PG8_SA(0, 1), a2 + hstepA, voffA);
;             PG8_WAIT_V(8); PG8_WAIT_L(0); PG8_BAR; PG8_MMA(0, 0, At, B0); PG8_MMA(0, 1, At, B1); PG8_BAR; PG8_SCHED;
;             PG8_LDA(At, 1, 1); PG8_STAGE(PG8_SB(1, 0), b3, voffB); PG8_STAGE(PG8_SB(1, 1), b3 + hstepB, voffB); PG8_STAGE(PG8_SA(1, 0), a3, voffA);
;             PG8_WAIT_V(8); PG8_WAIT_L(0); PG8_BAR; PG8_MMA(1, 0, At, B0); PG8_MMA(1, 1, At, B1); PG8_BAR; PG8_SCHED;
.LBB0_294:
	s_add_u32 s48, s46, 0xfffc0080
	s_addc_u32 s49, s47, -1
	s_add_i32 s63, 0, 0x10000
	s_cmp_eq_u32 s62, 12
	s_cselect_b32 s51, s7, s49
	s_cselect_b32 s50, s23, s48
	s_cselect_b32 s49, s21, s61
	s_cselect_b32 s48, s59, s60
	s_add_i32 s66, 0, 0x14000
	v_add_u32_e32 v146, s63, v175
	v_add_u32_e32 v170, s66, v175
	ds_read_b128 v[134:137], v146
	ds_read_b128 v[138:141], v146 offset:1024
	ds_read_b128 v[142:145], v146 offset:2048
	ds_read_b128 v[146:149], v146 offset:3072
	ds_read_b128 v[158:161], v170
	ds_read_b128 v[162:165], v170 offset:1024
	ds_read_b128 v[166:169], v170 offset:2048
	ds_read_b128 v[170:173], v170 offset:3072
	v_lshl_add_u64 v[200:201], s[46:47], 0, v[154:155]
	s_add_i32 m0, s39, 0xc000
	ds_read_b128 v[180:183], v179
	ds_read_b128 v[184:187], v179 offset:1024
	ds_read_b128 v[188:191], v179 offset:2048
	ds_read_b128 v[192:195], v179 offset:3072
	ds_read_b128 v[196:199], v179 offset:4096
	ds_read_b128 v[212:215], v179 offset:5120
	ds_read_b128 v[216:219], v179 offset:6144
	ds_read_b128 v[220:223], v179 offset:7168
	global_load_lds_dwordx4 v[200:201], off
	v_lshl_add_u64 v[200:201], s[46:47], 0, v[156:157]
	s_add_i32 m0, s39, 0xe000
	s_nop 0
	global_load_lds_dwordx4 v[200:201], off
	s_setprio 1
	s_waitcnt vmcnt(8) lgkmcnt(0)
	s_barrier
	v_mfma_f32_16x16x32_bf16 v[130:133], v[134:137], v[180:183], v[130:133]
	v_mfma_f32_16x16x32_bf16 v[126:129], v[142:145], v[180:183], v[126:129]
	v_mfma_f32_16x16x32_bf16 v[118:121], v[134:137], v[188:191], v[118:121]
	v_mfma_f32_16x16x32_bf16 v[110:113], v[142:145], v[188:191], v[110:113]
	v_mfma_f32_16x16x32_bf16 v[102:105], v[134:137], v[196:199], v[102:105]
	v_mfma_f32_16x16x32_bf16 v[94:97], v[142:145], v[196:199], v[94:97]
	v_mfma_f32_16x16x32_bf16 v[86:89], v[134:137], v[216:219], v[86:89]
	v_mfma_f32_16x16x32_bf16 v[78:81], v[142:145], v[216:219], v[78:81]
	v_mfma_f32_16x16x32_bf16 v[130:133], v[138:141], v[184:187], v[130:133]
	v_mfma_f32_16x16x32_bf16 v[126:129], v[146:149], v[184:187], v[126:129]
	v_mfma_f32_16x16x32_bf16 v[118:121], v[138:141], v[192:195], v[118:121]
	v_mfma_f32_16x16x32_bf16 v[110:113], v[146:149], v[192:195], v[110:113]
	v_mfma_f32_16x16x32_bf16 v[102:105], v[138:141], v[212:215], v[102:105]
	v_mfma_f32_16x16x32_bf16 v[94:97], v[146:149], v[212:215], v[94:97]
	v_mfma_f32_16x16x32_bf16 v[86:89], v[138:141], v[220:223], v[86:89]
	v_mfma_f32_16x16x32_bf16 v[78:81], v[146:149], v[220:223], v[78:81]
	s_setprio 0
	s_setprio 1
	v_mfma_f32_16x16x32_bf16 v[122:125], v[158:161], v[180:183], v[122:125]
	v_mfma_f32_16x16x32_bf16 v[114:117], v[166:169], v[180:183], v[114:117]
	v_mfma_f32_16x16x32_bf16 v[106:109], v[158:161], v[188:191], v[106:109]
	v_mfma_f32_16x16x32_bf16 v[98:101], v[166:169], v[188:191], v[98:101]
	v_mfma_f32_16x16x32_bf16 v[90:93], v[158:161], v[196:199], v[90:93]
	v_mfma_f32_16x16x32_bf16 v[82:85], v[166:169], v[196:199], v[82:85]
	v_mfma_f32_16x16x32_bf16 v[74:77], v[158:161], v[216:219], v[74:77]
	v_mfma_f32_16x16x32_bf16 v[70:73], v[166:169], v[216:219], v[70:73]
	v_mfma_f32_16x16x32_bf16 v[122:125], v[162:165], v[184:187], v[122:125]
	v_mfma_f32_16x16x32_bf16 v[114:117], v[170:173], v[184:187], v[114:117]
	v_mfma_f32_16x16x32_bf16 v[106:109], v[162:165], v[192:195], v[106:109]
	v_mfma_f32_16x16x32_bf16 v[98:101], v[170:173], v[192:195], v[98:101]
	v_mfma_f32_16x16x32_bf16 v[90:93], v[162:165], v[212:215], v[90:93]
	v_mfma_f32_16x16x32_bf16 v[82:85], v[170:173], v[212:215], v[82:85]
	v_mfma_f32_16x16x32_bf16 v[74:77], v[162:165], v[220:223], v[74:77]
	s_setprio 0
	v_mfma_f32_16x16x32_bf16 v[70:73], v[170:173], v[220:223], v[70:73]
	s_barrier
	s_add_i32 s63, s63, s1
	v_lshl_add_u64 v[200:201], s[48:49], 0, v[0:1]
	s_mov_b32 m0, s63
	ds_read_b128 v[180:183], v179 offset:16384
	ds_read_b128 v[184:187], v179 offset:17408
	ds_read_b128 v[188:191], v179 offset:18432
	ds_read_b128 v[192:195], v179 offset:19456
	ds_read_b128 v[196:199], v179 offset:20480
	ds_read_b128 v[212:215], v179 offset:21504
	ds_read_b128 v[216:219], v179 offset:22528
	ds_read_b128 v[220:223], v179 offset:23552
	global_load_lds_dwordx4 v[200:201], off
	s_add_i32 m0, s63, 0x2000
	s_add_u32 s64, s48, 0x40000
	v_lshl_add_u64 v[224:225], s[48:49], 0, v[14:15]
	s_addc_u32 s65, s49, 0
	s_add_i32 s63, s66, s1
	global_load_lds_dwordx4 v[224:225], off
	v_lshl_add_u64 v[226:227], s[64:65], 0, v[0:1]
	s_mov_b32 m0, s63
	v_lshl_add_u64 v[228:229], s[50:51], 0, v[150:151]
	global_load_lds_dwordx4 v[226:227], off
	v_lshl_add_u64 v[226:227], s[64:65], 0, v[14:15]
	s_add_i32 m0, s63, 0x2000
	s_nop 0
	global_load_lds_dwordx4 v[226:227], off
	v_lshl_add_u64 v[226:227], s[50:51], 0, v[152:153]
	s_mov_b32 m0, s39
	s_nop 0
	global_load_lds_dwordx4 v[226:227], off
	s_mov_b32 m0, s52
	s_nop 0
	global_load_lds_dwordx4 v[228:229], off
	s_setprio 1
	s_waitcnt vmcnt(8) lgkmcnt(0)
	s_barrier
; #define PG8_STAGE(bufoff, gbase, voff) do { _Pragma("unroll") for (int _i = 0; _i < 2; ++_i) \
;         __builtin_amdgcn_global_load_lds((const unsigned*)((const char*)(gbase) + (voff)[_i]), (LAS unsigned*)(lds + (bufoff) + ldsw + _i * 8192), 16, 0, 0); } while (0)
; #define PG8_LDA(dst, b, h) do { _Pragma("unroll") for (int m = 0; m < 4; ++m) _Pragma("unroll") for (int k = 0; k < 2; ++k) dst[m][k] = *(const LAS bf16x8*)(lds + PG8_SA(b, h) + aoff + m * 2048 + k * 1024); } while (0)
; #define PG8_LDB(dst, b, h) do { _Pragma("unroll") for (int n = 0; n < 2; ++n) _Pragma("unroll") for (int k = 0; k < 2; ++k) dst[n][k] = *(const LAS bf16x8*)(lds + PG8_SB(b, h) + boff + n * 2048 + k * 1024); } while (0)
; #define PG8_MMA(ai, bj, At, Bt) do { __builtin_amdgcn_s_setprio(1); _Pragma("unroll") for (int m = 0; m < 4; ++m) _Pragma("unroll") for (int n = 0; n < 2; ++n) _Pragma("unroll") for (int k = 0; k < 2; ++k) \
;         acc[ai][bj][m][n] = __builtin_amdgcn_mfma_f32_16x16x32_bf16(Bt[n][k], At[m][k], acc[ai][bj][m][n], 0, 0, 0); __builtin_amdgcn_s_setprio(0); } while (0)
; #define PG8_WAIT_V(n) asm volatile("s_waitcnt vmcnt(" #n ")" ::: "memory")
; #define PG8_BAR __builtin_amdgcn_s_barrier()
; template <class Epi, bool SEG>
; __device__ __forceinline__ void gemm_phase(LAS unsigned char* lds, const Gemm g, const int G, const int cidx, const Epi& E) {
;     ...
;             PG8_LDB(B0, 0, 0); PG8_LDB(B1, 0, 1); PG8_SCHED; PG8_LDA(At, 0, 0); PG8_STAGE(PG8_SA(1, 1), a1 + hstepA, voffA);
;             PG8_WAIT_V(8); PG8_WAIT_L(0); PG8_BAR; PG8_MMA(0, 0, At, B0); PG8_MMA(0, 1, At, B1); PG8_BAR; PG8_SCHED;
;             PG8_LDA(At, 0, 1); PG8_STAGE(PG8_SB(0, 0), b2, voffB); PG8_STAGE(PG8_SB(0, 1), b2 + hstepB, voffB); PG8_STAGE(PG8_SA(0, 0), a2, voffA);
;             PG8_WAIT_V(8); PG8_WAIT_L(0); PG8_BAR; PG8_MMA(1, 0, At, B0); PG8_MMA(1, 1, At, B1); PG8_BAR; PG8_SCHED;
;             PG8_LDB(B0, 1, 0); PG8_LDB(B1, 1, 1); PG8_SCHED; PG8_LDA(At, 1, 0); PG8_STAGE(PG8_SA(0, 1), a2 + hstepA, voffA);
;             PG8_WAIT_V(8); PG8_WAIT_L(0); PG8_BAR; PG8_MMA(0, 0, At, B0); PG8_MMA(0, 1, At, B1); PG8_BAR; PG8_SCHED;
;             PG8_LDA(At, 1, 1); PG8_STAGE(PG8_SB(1, 0), b3, voffB); PG8_STAGE(PG8_SB(1, 1), b3 + hstepB, voffB); PG8_STAGE(PG8_SA(1, 0), a3, voffA);
;             PG8_WAIT_V(8); PG8_WAIT_L(0); PG8_BAR; PG8_MMA(1, 0, At, B0); PG8_MMA(1, 1, At, B1); PG8_BAR; PG8_SCHED;
	v_mfma_f32_16x16x32_bf16 v[66:69], v[134:137], v[180:183], v[66:69]
	v_mfma_f32_16x16x32_bf16 v[62:65], v[142:145], v[180:183], v[62:65]
	v_mfma_f32_16x16x32_bf16 v[54:57], v[134:137], v[188:191], v[54:57]
	v_mfma_f32_16x16x32_bf16 v[46:49], v[142:145], v[188:191], v[46:49]
	v_mfma_f32_16x16x32_bf16 v[38:41], v[134:137], v[196:199], v[38:41]
	v_mfma_f32_16x16x32_bf16 v[30:33], v[142:145], v[196:199], v[30:33]
	v_mfma_f32_16x16x32_bf16 v[22:25], v[134:137], v[216:219], v[22:25]
	v_mfma_f32_16x16x32_bf16 v[10:13], v[142:145], v[216:219], v[10:13]
	v_mfma_f32_16x16x32_bf16 v[66:69], v[138:141], v[184:187], v[66:69]
	v_mfma_f32_16x16x32_bf16 v[62:65], v[146:149], v[184:187], v[62:65]
	v_mfma_f32_16x16x32_bf16 v[54:57], v[138:141], v[192:195], v[54:57]
	v_mfma_f32_16x16x32_bf16 v[46:49], v[146:149], v[192:195], v[46:49]
	v_mfma_f32_16x16x32_bf16 v[38:41], v[138:141], v[212:215], v[38:41]
	v_mfma_f32_16x16x32_bf16 v[30:33], v[146:149], v[212:215], v[30:33]
	v_mfma_f32_16x16x32_bf16 v[22:25], v[138:141], v[220:223], v[22:25]
	v_mfma_f32_16x16x32_bf16 v[10:13], v[146:149], v[220:223], v[10:13]
	s_setprio 0
	s_setprio 1
	v_mfma_f32_16x16x32_bf16 v[58:61], v[158:161], v[180:183], v[58:61]
	v_mfma_f32_16x16x32_bf16 v[50:53], v[166:169], v[180:183], v[50:53]
	v_mfma_f32_16x16x32_bf16 v[42:45], v[158:161], v[188:191], v[42:45]
	v_mfma_f32_16x16x32_bf16 v[34:37], v[166:169], v[188:191], v[34:37]
	v_mfma_f32_16x16x32_bf16 v[26:29], v[158:161], v[196:199], v[26:29]
	v_mfma_f32_16x16x32_bf16 v[18:21], v[166:169], v[196:199], v[18:21]
	v_mfma_f32_16x16x32_bf16 v[6:9], v[158:161], v[216:219], v[6:9]
	v_mfma_f32_16x16x32_bf16 v[2:5], v[166:169], v[216:219], v[2:5]
	v_mfma_f32_16x16x32_bf16 v[58:61], v[162:165], v[184:187], v[58:61]
	v_mfma_f32_16x16x32_bf16 v[50:53], v[170:173], v[184:187], v[50:53]
	v_mfma_f32_16x16x32_bf16 v[42:45], v[162:165], v[192:195], v[42:45]
	v_mfma_f32_16x16x32_bf16 v[34:37], v[170:173], v[192:195], v[34:37]
	v_mfma_f32_16x16x32_bf16 v[26:29], v[162:165], v[212:215], v[26:29]
	v_mfma_f32_16x16x32_bf16 v[18:21], v[170:173], v[212:215], v[18:21]
	v_mfma_f32_16x16x32_bf16 v[6:9], v[162:165], v[220:223], v[6:9]
	s_setprio 0
	v_mfma_f32_16x16x32_bf16 v[2:5], v[170:173], v[220:223], v[2:5]
	s_barrier
	s_add_i32 s63, 0, 0x18000
	s_add_i32 s64, 0, 0x1c000
	v_add_u32_e32 v146, s63, v175
	v_add_u32_e32 v170, s64, v175
	ds_read_b128 v[134:137], v146
	ds_read_b128 v[138:141], v146 offset:1024
	ds_read_b128 v[142:145], v146 offset:2048
	ds_read_b128 v[146:149], v146 offset:3072
	ds_read_b128 v[158:161], v170
	ds_read_b128 v[162:165], v170 offset:1024
	ds_read_b128 v[166:169], v170 offset:2048
	ds_read_b128 v[170:173], v170 offset:3072
	s_add_u32 s50, s50, 0x40000
	s_addc_u32 s51, s51, 0
	s_mov_b32 m0, s53
	v_lshl_add_u64 v[244:245], s[50:51], 0, v[152:153]
	ds_read_b128 v[180:183], v179 offset:32768
	ds_read_b128 v[184:187], v179 offset:33792
	ds_read_b128 v[188:191], v179 offset:34816
	ds_read_b128 v[192:195], v179 offset:35840
	ds_read_b128 v[196:199], v179 offset:36864
	ds_read_b128 v[212:215], v179 offset:37888
	ds_read_b128 v[216:219], v179 offset:38912
	ds_read_b128 v[220:223], v179 offset:39936
	global_load_lds_dwordx4 v[244:245], off
	v_lshl_add_u64 v[244:245], s[50:51], 0, v[150:151]
	s_mov_b32 m0, s54
	s_nop 0
	global_load_lds_dwordx4 v[244:245], off
	s_setprio 1
	s_waitcnt vmcnt(8) lgkmcnt(0)
	s_barrier
	v_mfma_f32_16x16x32_bf16 v[130:133], v[134:137], v[180:183], v[130:133]
	v_mfma_f32_16x16x32_bf16 v[126:129], v[142:145], v[180:183], v[126:129]
	v_mfma_f32_16x16x32_bf16 v[118:121], v[134:137], v[188:191], v[118:121]
	v_mfma_f32_16x16x32_bf16 v[110:113], v[142:145], v[188:191], v[110:113]
	v_mfma_f32_16x16x32_bf16 v[102:105], v[134:137], v[196:199], v[102:105]
	v_mfma_f32_16x16x32_bf16 v[94:97], v[142:145], v[196:199], v[94:97]
	v_mfma_f32_16x16x32_bf16 v[86:89], v[134:137], v[216:219], v[86:89]
	v_mfma_f32_16x16x32_bf16 v[78:81], v[142:145], v[216:219], v[78:81]
	v_mfma_f32_16x16x32_bf16 v[130:133], v[138:141], v[184:187], v[130:133]
	v_mfma_f32_16x16x32_bf16 v[126:129], v[146:149], v[184:187], v[126:129]
	v_mfma_f32_16x16x32_bf16 v[118:121], v[138:141], v[192:195], v[118:121]
	v_mfma_f32_16x16x32_bf16 v[110:113], v[146:149], v[192:195], v[110:113]
	v_mfma_f32_16x16x32_bf16 v[102:105], v[138:141], v[212:215], v[102:105]
	v_mfma_f32_16x16x32_bf16 v[94:97], v[146:149], v[212:215], v[94:97]
	v_mfma_f32_16x16x32_bf16 v[86:89], v[138:141], v[220:223], v[86:89]
	v_mfma_f32_16x16x32_bf16 v[78:81], v[146:149], v[220:223], v[78:81]
	s_setprio 0
	s_setprio 1
	v_mfma_f32_16x16x32_bf16 v[122:125], v[158:161], v[180:183], v[122:125]
	v_mfma_f32_16x16x32_bf16 v[114:117], v[166:169], v[180:183], v[114:117]
	v_mfma_f32_16x16x32_bf16 v[106:109], v[158:161], v[188:191], v[106:109]
	v_mfma_f32_16x16x32_bf16 v[98:101], v[166:169], v[188:191], v[98:101]
	v_mfma_f32_16x16x32_bf16 v[90:93], v[158:161], v[196:199], v[90:93]
	v_mfma_f32_16x16x32_bf16 v[82:85], v[166:169], v[196:199], v[82:85]
	v_mfma_f32_16x16x32_bf16 v[74:77], v[158:161], v[216:219], v[74:77]
	v_mfma_f32_16x16x32_bf16 v[70:73], v[166:169], v[216:219], v[70:73]
	v_mfma_f32_16x16x32_bf16 v[122:125], v[162:165], v[184:187], v[122:125]
	v_mfma_f32_16x16x32_bf16 v[114:117], v[170:173], v[184:187], v[114:117]
	v_mfma_f32_16x16x32_bf16 v[106:109], v[162:165], v[192:195], v[106:109]
	v_mfma_f32_16x16x32_bf16 v[98:101], v[170:173], v[192:195], v[98:101]
	v_mfma_f32_16x16x32_bf16 v[90:93], v[162:165], v[212:215], v[90:93]
	v_mfma_f32_16x16x32_bf16 v[82:85], v[170:173], v[212:215], v[82:85]
	v_mfma_f32_16x16x32_bf16 v[74:77], v[162:165], v[220:223], v[74:77]
	s_setprio 0
	v_mfma_f32_16x16x32_bf16 v[70:73], v[170:173], v[220:223], v[70:73]
	s_barrier
; #define PG8_STAGE(bufoff, gbase, voff) do { _Pragma("unroll") for (int _i = 0; _i < 2; ++_i) \
;         __builtin_amdgcn_global_load_lds((const unsigned*)((const char*)(gbase) + (voff)[_i]), (LAS unsigned*)(lds + (bufoff) + ldsw + _i * 8192), 16, 0, 0); } while (0)
; #define PG8_LDA(dst, b, h) do { _Pragma("unroll") for (int m = 0; m < 4; ++m) _Pragma("unroll") for (int k = 0; k < 2; ++k) dst[m][k] = *(const LAS bf16x8*)(lds + PG8_SA(b, h) + aoff + m * 2048 + k * 1024); } while (0)
; #define PG8_LDB(dst, b, h) do { _Pragma("unroll") for (int n = 0; n < 2; ++n) _Pragma("unroll") for (int k = 0; k < 2; ++k) dst[n][k] = *(const LAS bf16x8*)(lds + PG8_SB(b, h) + boff + n * 2048 + k * 1024); } while (0)
; #define PG8_MMA(ai, bj, At, Bt) do { __builtin_amdgcn_s_setprio(1); _Pragma("unroll") for (int m = 0; m < 4; ++m) _Pragma("unroll") for (int n = 0; n < 2; ++n) _Pragma("unroll") for (int k = 0; k < 2; ++k) \
;         acc[ai][bj][m][n] = __builtin_amdgcn_mfma_f32_16x16x32_bf16(Bt[n][k], At[m][k], acc[ai][bj][m][n], 0, 0, 0); __builtin_amdgcn_s_setprio(0); } while (0)
; #define PG8_WAIT_V(n) asm volatile("s_waitcnt vmcnt(" #n ")" ::: "memory")
; #define PG8_BAR __builtin_amdgcn_s_barrier()
; template <class Epi, bool SEG>
; __device__ __forceinline__ void gemm_phase(LAS unsigned char* lds, const Gemm g, const int G, const int cidx, const Epi& E) {
;     ...
;             PG8_LDB(B0, 0, 0); PG8_LDB(B1, 0, 1); PG8_SCHED; PG8_LDA(At, 0, 0); PG8_STAGE(PG8_SA(1, 1), a1 + hstepA, voffA);
;             PG8_WAIT_V(8); PG8_WAIT_L(0); PG8_BAR; PG8_MMA(0, 0, At, B0); PG8_MMA(0, 1, At, B1); PG8_BAR; PG8_SCHED;
;             PG8_LDA(At, 0, 1); PG8_STAGE(PG8_SB(0, 0), b2, voffB); PG8_STAGE(PG8_SB(0, 1), b2 + hstepB, voffB); PG8_STAGE(PG8_SA(0, 0), a2, voffA);
;             PG8_WAIT_V(8); PG8_WAIT_L(0); PG8_BAR; PG8_MMA(1, 0, At, B0); PG8_MMA(1, 1, At, B1); PG8_BAR; PG8_SCHED;
;             PG8_LDB(B0, 1, 0); PG8_LDB(B1, 1, 1); PG8_SCHED; PG8_LDA(At, 1, 0); PG8_STAGE(PG8_SA(0, 1), a2 + hstepA, voffA);
;             PG8_WAIT_V(8); PG8_WAIT_L(0); PG8_BAR; PG8_MMA(0, 0, At, B0); PG8_MMA(0, 1, At, B1); PG8_BAR; PG8_SCHED;
;             PG8_LDA(At, 1, 1); PG8_STAGE(PG8_SB(1, 0), b3, voffB); PG8_STAGE(PG8_SB(1, 1), b3 + hstepB, voffB); PG8_STAGE(PG8_SA(1, 0), a3, voffA);
;             PG8_WAIT_V(8); PG8_WAIT_L(0); PG8_BAR; PG8_MMA(1, 0, At, B0); PG8_MMA(1, 1, At, B1); PG8_BAR; PG8_SCHED;
	s_add_i32 s50, s63, s1
	v_lshl_add_u64 v[200:201], v[200:201], 0, s[28:29]
	s_mov_b32 m0, s50
	ds_read_b128 v[180:183], v179 offset:49152
	ds_read_b128 v[184:187], v179 offset:50176
	ds_read_b128 v[188:191], v179 offset:51200
	ds_read_b128 v[192:195], v179 offset:52224
	ds_read_b128 v[196:199], v179 offset:53248
	ds_read_b128 v[212:215], v179 offset:54272
	ds_read_b128 v[216:219], v179 offset:55296
	ds_read_b128 v[220:223], v179 offset:56320
	global_load_lds_dwordx4 v[200:201], off
	s_add_i32 m0, s50, 0x2000
	s_add_u32 s48, s48, 0x40080
	v_lshl_add_u64 v[200:201], v[224:225], 0, s[28:29]
	s_addc_u32 s49, s49, 0
	s_add_i32 s50, s64, s1
	global_load_lds_dwordx4 v[200:201], off
	v_lshl_add_u64 v[200:201], s[48:49], 0, v[0:1]
	s_mov_b32 m0, s50
	s_nop 0
	global_load_lds_dwordx4 v[200:201], off
	v_lshl_add_u64 v[200:201], s[48:49], 0, v[14:15]
	s_add_i32 m0, s50, 0x2000
	s_nop 0
	global_load_lds_dwordx4 v[200:201], off
	v_lshl_add_u64 v[200:201], v[226:227], 0, s[28:29]
	s_mov_b32 m0, s55
	s_nop 0
	global_load_lds_dwordx4 v[200:201], off
	v_lshl_add_u64 v[200:201], v[228:229], 0, s[28:29]
	s_mov_b32 m0, s56
	s_nop 0
	global_load_lds_dwordx4 v[200:201], off
	s_setprio 1
	s_waitcnt vmcnt(8) lgkmcnt(0)
	s_barrier
	v_mfma_f32_16x16x32_bf16 v[66:69], v[134:137], v[180:183], v[66:69]
	v_mfma_f32_16x16x32_bf16 v[62:65], v[142:145], v[180:183], v[62:65]
	v_mfma_f32_16x16x32_bf16 v[54:57], v[134:137], v[188:191], v[54:57]
	v_mfma_f32_16x16x32_bf16 v[46:49], v[142:145], v[188:191], v[46:49]
	v_mfma_f32_16x16x32_bf16 v[38:41], v[134:137], v[196:199], v[38:41]
	v_mfma_f32_16x16x32_bf16 v[30:33], v[142:145], v[196:199], v[30:33]
	v_mfma_f32_16x16x32_bf16 v[22:25], v[134:137], v[216:219], v[22:25]
	v_mfma_f32_16x16x32_bf16 v[10:13], v[142:145], v[216:219], v[10:13]
	v_mfma_f32_16x16x32_bf16 v[66:69], v[138:141], v[184:187], v[66:69]
	v_mfma_f32_16x16x32_bf16 v[62:65], v[146:149], v[184:187], v[62:65]
	v_mfma_f32_16x16x32_bf16 v[54:57], v[138:141], v[192:195], v[54:57]
	v_mfma_f32_16x16x32_bf16 v[46:49], v[146:149], v[192:195], v[46:49]
	v_mfma_f32_16x16x32_bf16 v[38:41], v[138:141], v[212:215], v[38:41]
	v_mfma_f32_16x16x32_bf16 v[30:33], v[146:149], v[212:215], v[30:33]
	v_mfma_f32_16x16x32_bf16 v[22:25], v[138:141], v[220:223], v[22:25]
	v_mfma_f32_16x16x32_bf16 v[10:13], v[146:149], v[220:223], v[10:13]
	s_setprio 0
	s_setprio 1
	v_mfma_f32_16x16x32_bf16 v[58:61], v[158:161], v[180:183], v[58:61]
	v_mfma_f32_16x16x32_bf16 v[50:53], v[166:169], v[180:183], v[50:53]
	v_mfma_f32_16x16x32_bf16 v[42:45], v[158:161], v[188:191], v[42:45]
	v_mfma_f32_16x16x32_bf16 v[34:37], v[166:169], v[188:191], v[34:37]
	v_mfma_f32_16x16x32_bf16 v[26:29], v[158:161], v[196:199], v[26:29]
	v_mfma_f32_16x16x32_bf16 v[18:21], v[166:169], v[196:199], v[18:21]
	v_mfma_f32_16x16x32_bf16 v[6:9], v[158:161], v[216:219], v[6:9]
	v_mfma_f32_16x16x32_bf16 v[2:5], v[166:169], v[216:219], v[2:5]
	v_mfma_f32_16x16x32_bf16 v[58:61], v[162:165], v[184:187], v[58:61]
	v_mfma_f32_16x16x32_bf16 v[50:53], v[170:173], v[184:187], v[50:53]
	v_mfma_f32_16x16x32_bf16 v[42:45], v[162:165], v[192:195], v[42:45]
	v_mfma_f32_16x16x32_bf16 v[34:37], v[170:173], v[192:195], v[34:37]
	v_mfma_f32_16x16x32_bf16 v[26:29], v[162:165], v[212:215], v[26:29]
	v_mfma_f32_16x16x32_bf16 v[18:21], v[170:173], v[212:215], v[18:21]
	v_mfma_f32_16x16x32_bf16 v[6:9], v[162:165], v[220:223], v[6:9]
	s_setprio 0
	v_mfma_f32_16x16x32_bf16 v[2:5], v[170:173], v[220:223], v[2:5]
	s_barrier
	s_add_i32 s62, s62, 2
	s_add_u32 s46, s46, 0x100
	s_addc_u32 s47, s47, 0
	s_add_u32 s60, s60, 0x100
	s_addc_u32 s61, s61, 0
	s_cmp_gt_u32 s62, 13
	s_cbranch_scc0 .LBB0_294
	s_and_b64 vcc, exec, s[18:19]
	s_cbranch_vccz .LBB0_297
	s_barrier

; #define PG8_STAGE(bufoff, gbase, voff) do { _Pragma("unroll") for (int _i = 0; _i < 2; ++_i) \
;         __builtin_amdgcn_global_load_lds((const unsigned*)((const char*)(gbase) + (voff)[_i]), (LAS unsigned*)(lds + (bufoff) + ldsw + _i * 8192), 16, 0, 0); } while (0)
; #define PG8_LDA(dst, b, h) do { _Pragma("unroll") for (int m = 0; m < 4; ++m) _Pragma("unroll") for (int k = 0; k < 2; ++k) dst[m][k] = *(const LAS bf16x8*)(lds + PG8_SA(b, h) + aoff + m * 2048 + k * 1024); } while (0)
; #define PG8_LDB(dst, b, h) do { _Pragma("unroll") for (int n = 0; n < 2; ++n) _Pragma("unroll") for (int k = 0; k < 2; ++k) dst[n][k] = *(const LAS bf16x8*)(lds + PG8_SB(b, h) + boff + n * 2048 + k * 1024); } while (0)
; #define PG8_MMA(ai, bj, At, Bt) do { __builtin_amdgcn_s_setprio(1); _Pragma("unroll") for (int m = 0; m < 4; ++m) _Pragma("unroll") for (int n = 0; n < 2; ++n) _Pragma("unroll") for (int k = 0; k < 2; ++k) \
;         acc[ai][bj][m][n] = __builtin_amdgcn_mfma_f32_16x16x32_bf16(Bt[n][k], At[m][k], acc[ai][bj][m][n], 0, 0, 0); __builtin_amdgcn_s_setprio(0); } while (0)
; #define PG8_WAIT_V(n) asm volatile("s_waitcnt vmcnt(" #n ")" ::: "memory")
; #define PG8_BAR __builtin_amdgcn_s_barrier()
; template <class Epi, bool SEG>
; __device__ __forceinline__ void gemm_phase(LAS unsigned char* lds, const Gemm g, const int G, const int cidx, const Epi& E) {
;     ...
;             PG8_LDB(B0, 0, 0); PG8_LDB(B1, 0, 1); PG8_SCHED; PG8_LDA(At, 0, 0); PG8_STAGE(PG8_SA(1, 1), a1 + hstepA, voffA);
;             PG8_WAIT_V(8); PG8_WAIT_L(0); PG8_BAR; PG8_MMA(0, 0, At, B0); PG8_MMA(0, 1, At, B1); PG8_BAR; PG8_SCHED;
;             PG8_LDA(At, 0, 1); PG8_STAGE(PG8_SB(0, 0), b2, voffB); PG8_STAGE(PG8_SB(0, 1), b2 + hstepB, voffB); PG8_STAGE(PG8_SA(0, 0), a2, voffA);
;             PG8_WAIT_V(8); PG8_WAIT_L(0); PG8_BAR; PG8_MMA(1, 0, At, B0); PG8_MMA(1, 1, At, B1); PG8_BAR; PG8_SCHED;
;             PG8_LDB(B0, 1, 0); PG8_LDB(B1, 1, 1); PG8_SCHED; PG8_LDA(At, 1, 0); PG8_STAGE(PG8_SA(0, 1), a2 + hstepA, voffA);
;             PG8_WAIT_V(8); PG8_WAIT_L(0); PG8_BAR; PG8_MMA(0, 0, At, B0); PG8_MMA(0, 1, At, B1); PG8_BAR; PG8_SCHED;
;             PG8_LDA(At, 1, 1); PG8_STAGE(PG8_SB(1, 0), b3, voffB); PG8_STAGE(PG8_SB(1, 1), b3 + hstepB, voffB); PG8_STAGE(PG8_SA(1, 0), a3, voffA);
;             PG8_WAIT_V(8); PG8_WAIT_L(0); PG8_BAR; PG8_MMA(1, 0, At, B0); PG8_MMA(1, 1, At, B1); PG8_BAR; PG8_SCHED;
.LBB0_706:
	s_add_u32 s48, s40, 0xfffc0080
	s_addc_u32 s49, s41, -1
	s_add_i32 s59, 0, 0x10000
	s_cmp_eq_u32 s58, 12
	s_cselect_b32 s51, s19, s49
	s_cselect_b32 s50, s54, s48
	s_cselect_b32 s49, s17, s57
	s_cselect_b32 s48, s55, s56
	s_add_i32 s62, 0, 0x14000
	v_add_u32_e32 v146, s59, v228
	v_add_u32_e32 v162, s62, v228
	ds_read_b128 v[130:133], v146
	ds_read_b128 v[138:141], v146 offset:1024
	ds_read_b128 v[142:145], v146 offset:2048
	ds_read_b128 v[146:149], v146 offset:3072
	ds_read_b128 v[150:153], v162
	ds_read_b128 v[154:157], v162 offset:1024
	ds_read_b128 v[158:161], v162 offset:2048
	ds_read_b128 v[162:165], v162 offset:3072
	v_lshl_add_u64 v[216:217], s[40:41], 0, v[198:199]
	s_add_i32 m0, s30, 0xc000
	ds_read_b128 v[166:169], v244
	ds_read_b128 v[170:173], v244 offset:1024
	ds_read_b128 v[174:177], v244 offset:2048
	ds_read_b128 v[178:181], v244 offset:3072
	ds_read_b128 v[182:185], v244 offset:4096
	ds_read_b128 v[186:189], v244 offset:5120
	ds_read_b128 v[190:193], v244 offset:6144
	ds_read_b128 v[212:215], v244 offset:7168
	global_load_lds_dwordx4 v[216:217], off
	v_lshl_add_u64 v[216:217], s[40:41], 0, v[200:201]
	s_add_i32 m0, s30, 0xe000
	s_nop 0
	global_load_lds_dwordx4 v[216:217], off
	s_setprio 1
	s_waitcnt vmcnt(8) lgkmcnt(0)
	s_barrier
	v_mfma_f32_16x16x32_bf16 v[134:137], v[130:133], v[166:169], v[134:137]
	v_mfma_f32_16x16x32_bf16 v[126:129], v[142:145], v[166:169], v[126:129]
	v_mfma_f32_16x16x32_bf16 v[114:117], v[130:133], v[174:177], v[114:117]
	v_mfma_f32_16x16x32_bf16 v[110:113], v[142:145], v[174:177], v[110:113]
	v_mfma_f32_16x16x32_bf16 v[98:101], v[130:133], v[182:185], v[98:101]
	v_mfma_f32_16x16x32_bf16 v[94:97], v[142:145], v[182:185], v[94:97]
	v_mfma_f32_16x16x32_bf16 v[82:85], v[130:133], v[190:193], v[82:85]
	v_mfma_f32_16x16x32_bf16 v[78:81], v[142:145], v[190:193], v[78:81]
	v_mfma_f32_16x16x32_bf16 v[134:137], v[138:141], v[170:173], v[134:137]
	v_mfma_f32_16x16x32_bf16 v[126:129], v[146:149], v[170:173], v[126:129]
	v_mfma_f32_16x16x32_bf16 v[114:117], v[138:141], v[178:181], v[114:117]
	v_mfma_f32_16x16x32_bf16 v[110:113], v[146:149], v[178:181], v[110:113]
	v_mfma_f32_16x16x32_bf16 v[98:101], v[138:141], v[186:189], v[98:101]
	v_mfma_f32_16x16x32_bf16 v[94:97], v[146:149], v[186:189], v[94:97]
	v_mfma_f32_16x16x32_bf16 v[82:85], v[138:141], v[212:215], v[82:85]
	v_mfma_f32_16x16x32_bf16 v[78:81], v[146:149], v[212:215], v[78:81]
	s_setprio 0
	s_setprio 1
	v_mfma_f32_16x16x32_bf16 v[122:125], v[150:153], v[166:169], v[122:125]
	v_mfma_f32_16x16x32_bf16 v[118:121], v[158:161], v[166:169], v[118:121]
	v_mfma_f32_16x16x32_bf16 v[106:109], v[150:153], v[174:177], v[106:109]
	v_mfma_f32_16x16x32_bf16 v[102:105], v[158:161], v[174:177], v[102:105]
	v_mfma_f32_16x16x32_bf16 v[90:93], v[150:153], v[182:185], v[90:93]
	v_mfma_f32_16x16x32_bf16 v[86:89], v[158:161], v[182:185], v[86:89]
	v_mfma_f32_16x16x32_bf16 v[74:77], v[150:153], v[190:193], v[74:77]
	v_mfma_f32_16x16x32_bf16 v[70:73], v[158:161], v[190:193], v[70:73]
	v_mfma_f32_16x16x32_bf16 v[122:125], v[154:157], v[170:173], v[122:125]
	v_mfma_f32_16x16x32_bf16 v[118:121], v[162:165], v[170:173], v[118:121]
	v_mfma_f32_16x16x32_bf16 v[106:109], v[154:157], v[178:181], v[106:109]
	v_mfma_f32_16x16x32_bf16 v[102:105], v[162:165], v[178:181], v[102:105]
	v_mfma_f32_16x16x32_bf16 v[90:93], v[154:157], v[186:189], v[90:93]
	v_mfma_f32_16x16x32_bf16 v[86:89], v[162:165], v[186:189], v[86:89]
	v_mfma_f32_16x16x32_bf16 v[74:77], v[154:157], v[212:215], v[74:77]
	s_setprio 0
	v_mfma_f32_16x16x32_bf16 v[70:73], v[162:165], v[212:215], v[70:73]
	s_barrier
	s_add_i32 s59, s59, s9
	v_lshl_add_u64 v[216:217], s[48:49], 0, v[0:1]
	s_mov_b32 m0, s59
	ds_read_b128 v[166:169], v244 offset:16384
	ds_read_b128 v[170:173], v244 offset:17408
	ds_read_b128 v[174:177], v244 offset:18432
	ds_read_b128 v[178:181], v244 offset:19456
	ds_read_b128 v[182:185], v244 offset:20480
	ds_read_b128 v[186:189], v244 offset:21504
	ds_read_b128 v[190:193], v244 offset:22528
	ds_read_b128 v[212:215], v244 offset:23552
	global_load_lds_dwordx4 v[216:217], off
	s_add_i32 m0, s59, 0x2000
	s_add_u32 s60, s48, 0x40000
	v_lshl_add_u64 v[218:219], s[48:49], 0, v[14:15]
	s_addc_u32 s61, s49, 0
	s_add_i32 s59, s62, s9
	global_load_lds_dwordx4 v[218:219], off
	v_lshl_add_u64 v[220:221], s[60:61], 0, v[0:1]
	s_mov_b32 m0, s59
	v_lshl_add_u64 v[222:223], s[50:51], 0, v[194:195]
	global_load_lds_dwordx4 v[220:221], off
	v_lshl_add_u64 v[220:221], s[60:61], 0, v[14:15]
	s_add_i32 m0, s59, 0x2000
	s_nop 0
	global_load_lds_dwordx4 v[220:221], off
	v_lshl_add_u64 v[220:221], s[50:51], 0, v[196:197]
	s_mov_b32 m0, s30
	s_nop 0
	global_load_lds_dwordx4 v[220:221], off
	s_mov_b32 m0, s31
	s_nop 0
	global_load_lds_dwordx4 v[222:223], off
	s_setprio 1
	s_waitcnt vmcnt(8) lgkmcnt(0)
	s_barrier
; #define PG8_STAGE(bufoff, gbase, voff) do { _Pragma("unroll") for (int _i = 0; _i < 2; ++_i) \
;         __builtin_amdgcn_global_load_lds((const unsigned*)((const char*)(gbase) + (voff)[_i]), (LAS unsigned*)(lds + (bufoff) + ldsw + _i * 8192), 16, 0, 0); } while (0)
; #define PG8_LDA(dst, b, h) do { _Pragma("unroll") for (int m = 0; m < 4; ++m) _Pragma("unroll") for (int k = 0; k < 2; ++k) dst[m][k] = *(const LAS bf16x8*)(lds + PG8_SA(b, h) + aoff + m * 2048 + k * 1024); } while (0)
; #define PG8_LDB(dst, b, h) do { _Pragma("unroll") for (int n = 0; n < 2; ++n) _Pragma("unroll") for (int k = 0; k < 2; ++k) dst[n][k] = *(const LAS bf16x8*)(lds + PG8_SB(b, h) + boff + n * 2048 + k * 1024); } while (0)
; #define PG8_MMA(ai, bj, At, Bt) do { __builtin_amdgcn_s_setprio(1); _Pragma("unroll") for (int m = 0; m < 4; ++m) _Pragma("unroll") for (int n = 0; n < 2; ++n) _Pragma("unroll") for (int k = 0; k < 2; ++k) \
;         acc[ai][bj][m][n] = __builtin_amdgcn_mfma_f32_16x16x32_bf16(Bt[n][k], At[m][k], acc[ai][bj][m][n], 0, 0, 0); __builtin_amdgcn_s_setprio(0); } while (0)
; #define PG8_WAIT_V(n) asm volatile("s_waitcnt vmcnt(" #n ")" ::: "memory")
; #define PG8_BAR __builtin_amdgcn_s_barrier()
; template <class Epi, bool SEG>
; __device__ __forceinline__ void gemm_phase(LAS unsigned char* lds, const Gemm g, const int G, const int cidx, const Epi& E) {
;     ...
;             PG8_LDB(B0, 0, 0); PG8_LDB(B1, 0, 1); PG8_SCHED; PG8_LDA(At, 0, 0); PG8_STAGE(PG8_SA(1, 1), a1 + hstepA, voffA);
;             PG8_WAIT_V(8); PG8_WAIT_L(0); PG8_BAR; PG8_MMA(0, 0, At, B0); PG8_MMA(0, 1, At, B1); PG8_BAR; PG8_SCHED;
;             PG8_LDA(At, 0, 1); PG8_STAGE(PG8_SB(0, 0), b2, voffB); PG8_STAGE(PG8_SB(0, 1), b2 + hstepB, voffB); PG8_STAGE(PG8_SA(0, 0), a2, voffA);
;             PG8_WAIT_V(8); PG8_WAIT_L(0); PG8_BAR; PG8_MMA(1, 0, At, B0); PG8_MMA(1, 1, At, B1); PG8_BAR; PG8_SCHED;
;             PG8_LDB(B0, 1, 0); PG8_LDB(B1, 1, 1); PG8_SCHED; PG8_LDA(At, 1, 0); PG8_STAGE(PG8_SA(0, 1), a2 + hstepA, voffA);
;             PG8_WAIT_V(8); PG8_WAIT_L(0); PG8_BAR; PG8_MMA(0, 0, At, B0); PG8_MMA(0, 1, At, B1); PG8_BAR; PG8_SCHED;
;             PG8_LDA(At, 1, 1); PG8_STAGE(PG8_SB(1, 0), b3, voffB); PG8_STAGE(PG8_SB(1, 1), b3 + hstepB, voffB); PG8_STAGE(PG8_SA(1, 0), a3, voffA);
;             PG8_WAIT_V(8); PG8_WAIT_L(0); PG8_BAR; PG8_MMA(1, 0, At, B0); PG8_MMA(1, 1, At, B1); PG8_BAR; PG8_SCHED;
	v_mfma_f32_16x16x32_bf16 v[66:69], v[130:133], v[166:169], v[66:69]
	v_mfma_f32_16x16x32_bf16 v[62:65], v[142:145], v[166:169], v[62:65]
	v_mfma_f32_16x16x32_bf16 v[50:53], v[130:133], v[174:177], v[50:53]
	v_mfma_f32_16x16x32_bf16 v[46:49], v[142:145], v[174:177], v[46:49]
	v_mfma_f32_16x16x32_bf16 v[34:37], v[130:133], v[182:185], v[34:37]
	v_mfma_f32_16x16x32_bf16 v[30:33], v[142:145], v[182:185], v[30:33]
	v_mfma_f32_16x16x32_bf16 v[18:21], v[130:133], v[190:193], v[18:21]
	v_mfma_f32_16x16x32_bf16 v[10:13], v[142:145], v[190:193], v[10:13]
	v_mfma_f32_16x16x32_bf16 v[66:69], v[138:141], v[170:173], v[66:69]
	v_mfma_f32_16x16x32_bf16 v[62:65], v[146:149], v[170:173], v[62:65]
	v_mfma_f32_16x16x32_bf16 v[50:53], v[138:141], v[178:181], v[50:53]
	v_mfma_f32_16x16x32_bf16 v[46:49], v[146:149], v[178:181], v[46:49]
	v_mfma_f32_16x16x32_bf16 v[34:37], v[138:141], v[186:189], v[34:37]
	v_mfma_f32_16x16x32_bf16 v[30:33], v[146:149], v[186:189], v[30:33]
	v_mfma_f32_16x16x32_bf16 v[18:21], v[138:141], v[212:215], v[18:21]
	v_mfma_f32_16x16x32_bf16 v[10:13], v[146:149], v[212:215], v[10:13]
	s_setprio 0
	s_setprio 1
	v_mfma_f32_16x16x32_bf16 v[58:61], v[150:153], v[166:169], v[58:61]
	v_mfma_f32_16x16x32_bf16 v[54:57], v[158:161], v[166:169], v[54:57]
	v_mfma_f32_16x16x32_bf16 v[42:45], v[150:153], v[174:177], v[42:45]
	v_mfma_f32_16x16x32_bf16 v[38:41], v[158:161], v[174:177], v[38:41]
	v_mfma_f32_16x16x32_bf16 v[26:29], v[150:153], v[182:185], v[26:29]
	v_mfma_f32_16x16x32_bf16 v[22:25], v[158:161], v[182:185], v[22:25]
	v_mfma_f32_16x16x32_bf16 v[6:9], v[150:153], v[190:193], v[6:9]
	v_mfma_f32_16x16x32_bf16 v[2:5], v[158:161], v[190:193], v[2:5]
	v_mfma_f32_16x16x32_bf16 v[58:61], v[154:157], v[170:173], v[58:61]
	v_mfma_f32_16x16x32_bf16 v[54:57], v[162:165], v[170:173], v[54:57]
	v_mfma_f32_16x16x32_bf16 v[42:45], v[154:157], v[178:181], v[42:45]
	v_mfma_f32_16x16x32_bf16 v[38:41], v[162:165], v[178:181], v[38:41]
	v_mfma_f32_16x16x32_bf16 v[26:29], v[154:157], v[186:189], v[26:29]
	v_mfma_f32_16x16x32_bf16 v[22:25], v[162:165], v[186:189], v[22:25]
	v_mfma_f32_16x16x32_bf16 v[6:9], v[154:157], v[212:215], v[6:9]
	s_setprio 0
	v_mfma_f32_16x16x32_bf16 v[2:5], v[162:165], v[212:215], v[2:5]
	s_barrier
	s_add_i32 s59, 0, 0x18000
	s_add_i32 s60, 0, 0x1c000
	v_add_u32_e32 v146, s59, v228
	v_add_u32_e32 v162, s60, v228
	ds_read_b128 v[130:133], v146
	ds_read_b128 v[138:141], v146 offset:1024
	ds_read_b128 v[142:145], v146 offset:2048
	ds_read_b128 v[146:149], v146 offset:3072
	ds_read_b128 v[150:153], v162
	ds_read_b128 v[154:157], v162 offset:1024
	ds_read_b128 v[158:161], v162 offset:2048
	ds_read_b128 v[162:165], v162 offset:3072
	s_add_u32 s50, s50, 0x40000
	s_addc_u32 s51, s51, 0
	s_mov_b32 m0, s36
	v_lshl_add_u64 v[224:225], s[50:51], 0, v[196:197]
	ds_read_b128 v[166:169], v244 offset:32768
	ds_read_b128 v[170:173], v244 offset:33792
	ds_read_b128 v[174:177], v244 offset:34816
	ds_read_b128 v[178:181], v244 offset:35840
	ds_read_b128 v[182:185], v244 offset:36864
	ds_read_b128 v[186:189], v244 offset:37888
	ds_read_b128 v[190:193], v244 offset:38912
	ds_read_b128 v[212:215], v244 offset:39936
	global_load_lds_dwordx4 v[224:225], off
	v_lshl_add_u64 v[224:225], s[50:51], 0, v[194:195]
	s_mov_b32 m0, s38
	s_nop 0
	global_load_lds_dwordx4 v[224:225], off
	s_setprio 1
	s_waitcnt vmcnt(8) lgkmcnt(0)
	s_barrier
	v_mfma_f32_16x16x32_bf16 v[134:137], v[130:133], v[166:169], v[134:137]
	v_mfma_f32_16x16x32_bf16 v[126:129], v[142:145], v[166:169], v[126:129]
	v_mfma_f32_16x16x32_bf16 v[114:117], v[130:133], v[174:177], v[114:117]
	v_mfma_f32_16x16x32_bf16 v[110:113], v[142:145], v[174:177], v[110:113]
	v_mfma_f32_16x16x32_bf16 v[98:101], v[130:133], v[182:185], v[98:101]
	v_mfma_f32_16x16x32_bf16 v[94:97], v[142:145], v[182:185], v[94:97]
	v_mfma_f32_16x16x32_bf16 v[82:85], v[130:133], v[190:193], v[82:85]
	v_mfma_f32_16x16x32_bf16 v[78:81], v[142:145], v[190:193], v[78:81]
	v_mfma_f32_16x16x32_bf16 v[134:137], v[138:141], v[170:173], v[134:137]
	v_mfma_f32_16x16x32_bf16 v[126:129], v[146:149], v[170:173], v[126:129]
	v_mfma_f32_16x16x32_bf16 v[114:117], v[138:141], v[178:181], v[114:117]
	v_mfma_f32_16x16x32_bf16 v[110:113], v[146:149], v[178:181], v[110:113]
	v_mfma_f32_16x16x32_bf16 v[98:101], v[138:141], v[186:189], v[98:101]
	v_mfma_f32_16x16x32_bf16 v[94:97], v[146:149], v[186:189], v[94:97]
	v_mfma_f32_16x16x32_bf16 v[82:85], v[138:141], v[212:215], v[82:85]
	v_mfma_f32_16x16x32_bf16 v[78:81], v[146:149], v[212:215], v[78:81]
	s_setprio 0
	s_setprio 1
	v_mfma_f32_16x16x32_bf16 v[122:125], v[150:153], v[166:169], v[122:125]
	v_mfma_f32_16x16x32_bf16 v[118:121], v[158:161], v[166:169], v[118:121]
	v_mfma_f32_16x16x32_bf16 v[106:109], v[150:153], v[174:177], v[106:109]
	v_mfma_f32_16x16x32_bf16 v[102:105], v[158:161], v[174:177], v[102:105]
	v_mfma_f32_16x16x32_bf16 v[90:93], v[150:153], v[182:185], v[90:93]
	v_mfma_f32_16x16x32_bf16 v[86:89], v[158:161], v[182:185], v[86:89]
	v_mfma_f32_16x16x32_bf16 v[74:77], v[150:153], v[190:193], v[74:77]
	v_mfma_f32_16x16x32_bf16 v[70:73], v[158:161], v[190:193], v[70:73]
	v_mfma_f32_16x16x32_bf16 v[122:125], v[154:157], v[170:173], v[122:125]
	v_mfma_f32_16x16x32_bf16 v[118:121], v[162:165], v[170:173], v[118:121]
	v_mfma_f32_16x16x32_bf16 v[106:109], v[154:157], v[178:181], v[106:109]
	v_mfma_f32_16x16x32_bf16 v[102:105], v[162:165], v[178:181], v[102:105]
	v_mfma_f32_16x16x32_bf16 v[90:93], v[154:157], v[186:189], v[90:93]
	v_mfma_f32_16x16x32_bf16 v[86:89], v[162:165], v[186:189], v[86:89]
	v_mfma_f32_16x16x32_bf16 v[74:77], v[154:157], v[212:215], v[74:77]
	s_setprio 0
	v_mfma_f32_16x16x32_bf16 v[70:73], v[162:165], v[212:215], v[70:73]
	s_barrier
; #define PG8_STAGE(bufoff, gbase, voff) do { _Pragma("unroll") for (int _i = 0; _i < 2; ++_i) \
;         __builtin_amdgcn_global_load_lds((const unsigned*)((const char*)(gbase) + (voff)[_i]), (LAS unsigned*)(lds + (bufoff) + ldsw + _i * 8192), 16, 0, 0); } while (0)
; #define PG8_LDA(dst, b, h) do { _Pragma("unroll") for (int m = 0; m < 4; ++m) _Pragma("unroll") for (int k = 0; k < 2; ++k) dst[m][k] = *(const LAS bf16x8*)(lds + PG8_SA(b, h) + aoff + m * 2048 + k * 1024); } while (0)
; #define PG8_LDB(dst, b, h) do { _Pragma("unroll") for (int n = 0; n < 2; ++n) _Pragma("unroll") for (int k = 0; k < 2; ++k) dst[n][k] = *(const LAS bf16x8*)(lds + PG8_SB(b, h) + boff + n * 2048 + k * 1024); } while (0)
; #define PG8_MMA(ai, bj, At, Bt) do { __builtin_amdgcn_s_setprio(1); _Pragma("unroll") for (int m = 0; m < 4; ++m) _Pragma("unroll") for (int n = 0; n < 2; ++n) _Pragma("unroll") for (int k = 0; k < 2; ++k) \
;         acc[ai][bj][m][n] = __builtin_amdgcn_mfma_f32_16x16x32_bf16(Bt[n][k], At[m][k], acc[ai][bj][m][n], 0, 0, 0); __builtin_amdgcn_s_setprio(0); } while (0)
; #define PG8_WAIT_V(n) asm volatile("s_waitcnt vmcnt(" #n ")" ::: "memory")
; #define PG8_BAR __builtin_amdgcn_s_barrier()
; template <class Epi, bool SEG>
; __device__ __forceinline__ void gemm_phase(LAS unsigned char* lds, const Gemm g, const int G, const int cidx, const Epi& E) {
;     ...
;             PG8_LDB(B0, 0, 0); PG8_LDB(B1, 0, 1); PG8_SCHED; PG8_LDA(At, 0, 0); PG8_STAGE(PG8_SA(1, 1), a1 + hstepA, voffA);
;             PG8_WAIT_V(8); PG8_WAIT_L(0); PG8_BAR; PG8_MMA(0, 0, At, B0); PG8_MMA(0, 1, At, B1); PG8_BAR; PG8_SCHED;
;             PG8_LDA(At, 0, 1); PG8_STAGE(PG8_SB(0, 0), b2, voffB); PG8_STAGE(PG8_SB(0, 1), b2 + hstepB, voffB); PG8_STAGE(PG8_SA(0, 0), a2, voffA);
;             PG8_WAIT_V(8); PG8_WAIT_L(0); PG8_BAR; PG8_MMA(1, 0, At, B0); PG8_MMA(1, 1, At, B1); PG8_BAR; PG8_SCHED;
;             PG8_LDB(B0, 1, 0); PG8_LDB(B1, 1, 1); PG8_SCHED; PG8_LDA(At, 1, 0); PG8_STAGE(PG8_SA(0, 1), a2 + hstepA, voffA);
;             PG8_WAIT_V(8); PG8_WAIT_L(0); PG8_BAR; PG8_MMA(0, 0, At, B0); PG8_MMA(0, 1, At, B1); PG8_BAR; PG8_SCHED;
;             PG8_LDA(At, 1, 1); PG8_STAGE(PG8_SB(1, 0), b3, voffB); PG8_STAGE(PG8_SB(1, 1), b3 + hstepB, voffB); PG8_STAGE(PG8_SA(1, 0), a3, voffA);
;             PG8_WAIT_V(8); PG8_WAIT_L(0); PG8_BAR; PG8_MMA(1, 0, At, B0); PG8_MMA(1, 1, At, B1); PG8_BAR; PG8_SCHED;
	s_add_i32 s50, s59, s9
	v_lshl_add_u64 v[216:217], v[216:217], 0, s[28:29]
	s_mov_b32 m0, s50
	ds_read_b128 v[166:169], v244 offset:49152
	ds_read_b128 v[170:173], v244 offset:50176
	ds_read_b128 v[174:177], v244 offset:51200
	ds_read_b128 v[178:181], v244 offset:52224
	ds_read_b128 v[182:185], v244 offset:53248
	ds_read_b128 v[186:189], v244 offset:54272
	ds_read_b128 v[190:193], v244 offset:55296
	ds_read_b128 v[212:215], v244 offset:56320
	global_load_lds_dwordx4 v[216:217], off
	s_add_i32 m0, s50, 0x2000
	s_add_u32 s48, s48, 0x40080
	v_lshl_add_u64 v[216:217], v[218:219], 0, s[28:29]
	s_addc_u32 s49, s49, 0
	s_add_i32 s50, s60, s9
	global_load_lds_dwordx4 v[216:217], off
	v_lshl_add_u64 v[216:217], s[48:49], 0, v[0:1]
	s_mov_b32 m0, s50
	s_nop 0
	global_load_lds_dwordx4 v[216:217], off
	v_lshl_add_u64 v[216:217], s[48:49], 0, v[14:15]
	s_add_i32 m0, s50, 0x2000
	s_nop 0
	global_load_lds_dwordx4 v[216:217], off
	v_lshl_add_u64 v[216:217], v[220:221], 0, s[28:29]
	s_mov_b32 m0, s39
	s_nop 0
	global_load_lds_dwordx4 v[216:217], off
	v_lshl_add_u64 v[216:217], v[222:223], 0, s[28:29]
	s_mov_b32 m0, s52
	s_nop 0
	global_load_lds_dwordx4 v[216:217], off
	s_setprio 1
	s_waitcnt vmcnt(8) lgkmcnt(0)
	s_barrier
	v_mfma_f32_16x16x32_bf16 v[66:69], v[130:133], v[166:169], v[66:69]
	v_mfma_f32_16x16x32_bf16 v[62:65], v[142:145], v[166:169], v[62:65]
	v_mfma_f32_16x16x32_bf16 v[50:53], v[130:133], v[174:177], v[50:53]
	v_mfma_f32_16x16x32_bf16 v[46:49], v[142:145], v[174:177], v[46:49]
	v_mfma_f32_16x16x32_bf16 v[34:37], v[130:133], v[182:185], v[34:37]
	v_mfma_f32_16x16x32_bf16 v[30:33], v[142:145], v[182:185], v[30:33]
	v_mfma_f32_16x16x32_bf16 v[18:21], v[130:133], v[190:193], v[18:21]
	v_mfma_f32_16x16x32_bf16 v[10:13], v[142:145], v[190:193], v[10:13]
	v_mfma_f32_16x16x32_bf16 v[66:69], v[138:141], v[170:173], v[66:69]
	v_mfma_f32_16x16x32_bf16 v[62:65], v[146:149], v[170:173], v[62:65]
	v_mfma_f32_16x16x32_bf16 v[50:53], v[138:141], v[178:181], v[50:53]
	v_mfma_f32_16x16x32_bf16 v[46:49], v[146:149], v[178:181], v[46:49]
	v_mfma_f32_16x16x32_bf16 v[34:37], v[138:141], v[186:189], v[34:37]
	v_mfma_f32_16x16x32_bf16 v[30:33], v[146:149], v[186:189], v[30:33]
	v_mfma_f32_16x16x32_bf16 v[18:21], v[138:141], v[212:215], v[18:21]
	v_mfma_f32_16x16x32_bf16 v[10:13], v[146:149], v[212:215], v[10:13]
	s_setprio 0
	s_setprio 1
	v_mfma_f32_16x16x32_bf16 v[58:61], v[150:153], v[166:169], v[58:61]
	v_mfma_f32_16x16x32_bf16 v[54:57], v[158:161], v[166:169], v[54:57]
	v_mfma_f32_16x16x32_bf16 v[42:45], v[150:153], v[174:177], v[42:45]
	v_mfma_f32_16x16x32_bf16 v[38:41], v[158:161], v[174:177], v[38:41]
	v_mfma_f32_16x16x32_bf16 v[26:29], v[150:153], v[182:185], v[26:29]
	v_mfma_f32_16x16x32_bf16 v[22:25], v[158:161], v[182:185], v[22:25]
	v_mfma_f32_16x16x32_bf16 v[6:9], v[150:153], v[190:193], v[6:9]
	v_mfma_f32_16x16x32_bf16 v[2:5], v[158:161], v[190:193], v[2:5]
	v_mfma_f32_16x16x32_bf16 v[58:61], v[154:157], v[170:173], v[58:61]
	v_mfma_f32_16x16x32_bf16 v[54:57], v[162:165], v[170:173], v[54:57]
	v_mfma_f32_16x16x32_bf16 v[42:45], v[154:157], v[178:181], v[42:45]
	v_mfma_f32_16x16x32_bf16 v[38:41], v[162:165], v[178:181], v[38:41]
	v_mfma_f32_16x16x32_bf16 v[26:29], v[154:157], v[186:189], v[26:29]
	v_mfma_f32_16x16x32_bf16 v[22:25], v[162:165], v[186:189], v[22:25]
	v_mfma_f32_16x16x32_bf16 v[6:9], v[154:157], v[212:215], v[6:9]
	s_setprio 0
	v_mfma_f32_16x16x32_bf16 v[2:5], v[162:165], v[212:215], v[2:5]
	s_barrier
	s_add_i32 s58, s58, 2
	s_add_u32 s40, s40, 0x100
	s_addc_u32 s41, s41, 0
	s_add_u32 s56, s56, 0x100
	s_addc_u32 s57, s57, 0
	s_cmp_gt_u32 s58, 13
	s_cbranch_scc0 .LBB0_706
	s_and_b64 vcc, exec, s[12:13]
	s_cbranch_vccz .LBB0_709
	s_barrier

; #define PG8_STAGE(bufoff, gbase, voff) do { _Pragma("unroll") for (int _i = 0; _i < 2; ++_i) \
;         __builtin_amdgcn_global_load_lds((const unsigned*)((const char*)(gbase) + (voff)[_i]), (LAS unsigned*)(lds + (bufoff) + ldsw + _i * 8192), 16, 0, 0); } while (0)
; #define PG8_LDA(dst, b, h) do { _Pragma("unroll") for (int m = 0; m < 4; ++m) _Pragma("unroll") for (int k = 0; k < 2; ++k) dst[m][k] = *(const LAS bf16x8*)(lds + PG8_SA(b, h) + aoff + m * 2048 + k * 1024); } while (0)
; #define PG8_LDB(dst, b, h) do { _Pragma("unroll") for (int n = 0; n < 2; ++n) _Pragma("unroll") for (int k = 0; k < 2; ++k) dst[n][k] = *(const LAS bf16x8*)(lds + PG8_SB(b, h) + boff + n * 2048 + k * 1024); } while (0)
; #define PG8_MMA(ai, bj, At, Bt) do { __builtin_amdgcn_s_setprio(1); _Pragma("unroll") for (int m = 0; m < 4; ++m) _Pragma("unroll") for (int n = 0; n < 2; ++n) _Pragma("unroll") for (int k = 0; k < 2; ++k) \
;         acc[ai][bj][m][n] = __builtin_amdgcn_mfma_f32_16x16x32_bf16(Bt[n][k], At[m][k], acc[ai][bj][m][n], 0, 0, 0); __builtin_amdgcn_s_setprio(0); } while (0)
; #define PG8_WAIT_V(n) asm volatile("s_waitcnt vmcnt(" #n ")" ::: "memory")
; #define PG8_BAR __builtin_amdgcn_s_barrier()
; template <class Epi, bool SEG>
; __device__ __forceinline__ void gemm_phase(LAS unsigned char* lds, const Gemm g, const int G, const int cidx, const Epi& E) {
;     ...
;             PG8_LDB(B0, 0, 0); PG8_LDB(B1, 0, 1); PG8_SCHED; PG8_LDA(At, 0, 0); PG8_STAGE(PG8_SA(1, 1), a1 + hstepA, voffA);
;             PG8_WAIT_V(8); PG8_WAIT_L(0); PG8_BAR; PG8_MMA(0, 0, At, B0); PG8_MMA(0, 1, At, B1); PG8_BAR; PG8_SCHED;
;             PG8_LDA(At, 0, 1); PG8_STAGE(PG8_SB(0, 0), b2, voffB); PG8_STAGE(PG8_SB(0, 1), b2 + hstepB, voffB); PG8_STAGE(PG8_SA(0, 0), a2, voffA);
;             PG8_WAIT_V(8); PG8_WAIT_L(0); PG8_BAR; PG8_MMA(1, 0, At, B0); PG8_MMA(1, 1, At, B1); PG8_BAR; PG8_SCHED;
;             PG8_LDB(B0, 1, 0); PG8_LDB(B1, 1, 1); PG8_SCHED; PG8_LDA(At, 1, 0); PG8_STAGE(PG8_SA(0, 1), a2 + hstepA, voffA);
;             PG8_WAIT_V(8); PG8_WAIT_L(0); PG8_BAR; PG8_MMA(0, 0, At, B0); PG8_MMA(0, 1, At, B1); PG8_BAR; PG8_SCHED;
;             PG8_LDA(At, 1, 1); PG8_STAGE(PG8_SB(1, 0), b3, voffB); PG8_STAGE(PG8_SB(1, 1), b3 + hstepB, voffB); PG8_STAGE(PG8_SA(1, 0), a3, voffA);
;             PG8_WAIT_V(8); PG8_WAIT_L(0); PG8_BAR; PG8_MMA(1, 0, At, B0); PG8_MMA(1, 1, At, B1); PG8_BAR; PG8_SCHED;
.LBB0_786:
	s_add_u32 s22, s6, 0xfffc2080
	s_addc_u32 s23, s7, -1
	s_add_i32 s55, 0, 0x10000
	s_cmp_eq_u32 s54, 12
	s_cselect_b32 s41, s17, s23
	s_cselect_b32 s40, s16, s22
	s_cselect_b32 s23, s15, s53
	s_cselect_b32 s22, s21, s52
	s_add_i32 s58, 0, 0x14000
	v_add_u32_e32 v114, s55, v243
	v_add_u32_e32 v130, s58, v243
	ds_read_b128 v[102:105], v114
	ds_read_b128 v[106:109], v114 offset:1024
	ds_read_b128 v[110:113], v114 offset:2048
	ds_read_b128 v[114:117], v114 offset:3072
	ds_read_b128 v[118:121], v130
	ds_read_b128 v[122:125], v130 offset:1024
	ds_read_b128 v[126:129], v130 offset:2048
	ds_read_b128 v[130:133], v130 offset:3072
	v_lshl_add_u64 v[208:209], s[6:7], 0, v[198:199]
	s_add_i32 m0, s11, 0xc000
	ds_read_b128 v[166:169], v247
	ds_read_b128 v[170:173], v247 offset:1024
	ds_read_b128 v[174:177], v247 offset:2048
	ds_read_b128 v[178:181], v247 offset:3072
	ds_read_b128 v[182:185], v247 offset:4096
	ds_read_b128 v[186:189], v247 offset:5120
	ds_read_b128 v[212:215], v247 offset:6144
	ds_read_b128 v[216:219], v247 offset:7168
	global_load_lds_dwordx4 v[208:209], off
	v_lshl_add_u64 v[208:209], s[6:7], 0, v[200:201]
	s_add_i32 m0, s11, 0xe000
	s_nop 0
	global_load_lds_dwordx4 v[208:209], off
	s_setprio 1
	s_waitcnt vmcnt(8) lgkmcnt(0)
	s_barrier
	v_mfma_f32_16x16x32_bf16 v[162:165], v[102:105], v[166:169], v[162:165]
	v_mfma_f32_16x16x32_bf16 v[66:69], v[110:113], v[166:169], v[66:69]
	v_mfma_f32_16x16x32_bf16 v[158:161], v[102:105], v[174:177], v[158:161]
	v_mfma_f32_16x16x32_bf16 v[62:65], v[110:113], v[174:177], v[62:65]
	v_mfma_f32_16x16x32_bf16 v[146:149], v[102:105], v[182:185], v[146:149]
	v_mfma_f32_16x16x32_bf16 v[50:53], v[110:113], v[182:185], v[50:53]
	v_mfma_f32_16x16x32_bf16 v[138:141], v[102:105], v[212:215], v[138:141]
	v_mfma_f32_16x16x32_bf16 v[42:45], v[110:113], v[212:215], v[42:45]
	v_mfma_f32_16x16x32_bf16 v[162:165], v[106:109], v[170:173], v[162:165]
	v_mfma_f32_16x16x32_bf16 v[66:69], v[114:117], v[170:173], v[66:69]
	v_mfma_f32_16x16x32_bf16 v[158:161], v[106:109], v[178:181], v[158:161]
	v_mfma_f32_16x16x32_bf16 v[62:65], v[114:117], v[178:181], v[62:65]
	v_mfma_f32_16x16x32_bf16 v[146:149], v[106:109], v[186:189], v[146:149]
	v_mfma_f32_16x16x32_bf16 v[50:53], v[114:117], v[186:189], v[50:53]
	v_mfma_f32_16x16x32_bf16 v[138:141], v[106:109], v[216:219], v[138:141]
	v_mfma_f32_16x16x32_bf16 v[42:45], v[114:117], v[216:219], v[42:45]
	s_setprio 0
	s_setprio 1
	v_mfma_f32_16x16x32_bf16 v[154:157], v[118:121], v[166:169], v[154:157]
	v_mfma_f32_16x16x32_bf16 v[58:61], v[126:129], v[166:169], v[58:61]
	v_mfma_f32_16x16x32_bf16 v[150:153], v[118:121], v[174:177], v[150:153]
	v_mfma_f32_16x16x32_bf16 v[54:57], v[126:129], v[174:177], v[54:57]
	v_mfma_f32_16x16x32_bf16 v[142:145], v[118:121], v[182:185], v[142:145]
	v_mfma_f32_16x16x32_bf16 v[46:49], v[126:129], v[182:185], v[46:49]
	v_mfma_f32_16x16x32_bf16 v[134:137], v[118:121], v[212:215], v[134:137]
	v_mfma_f32_16x16x32_bf16 v[38:41], v[126:129], v[212:215], v[38:41]
	v_mfma_f32_16x16x32_bf16 v[154:157], v[122:125], v[170:173], v[154:157]
	v_mfma_f32_16x16x32_bf16 v[58:61], v[130:133], v[170:173], v[58:61]
	v_mfma_f32_16x16x32_bf16 v[150:153], v[122:125], v[178:181], v[150:153]
	v_mfma_f32_16x16x32_bf16 v[54:57], v[130:133], v[178:181], v[54:57]
	v_mfma_f32_16x16x32_bf16 v[142:145], v[122:125], v[186:189], v[142:145]
	v_mfma_f32_16x16x32_bf16 v[46:49], v[130:133], v[186:189], v[46:49]
	v_mfma_f32_16x16x32_bf16 v[134:137], v[122:125], v[216:219], v[134:137]
	s_setprio 0
	v_mfma_f32_16x16x32_bf16 v[38:41], v[130:133], v[216:219], v[38:41]
	s_barrier
	s_add_i32 s55, s55, s10
	v_lshl_add_u64 v[208:209], s[22:23], 0, v[0:1]
	s_mov_b32 m0, s55
	ds_read_b128 v[166:169], v247 offset:16384
	ds_read_b128 v[170:173], v247 offset:17408
	ds_read_b128 v[174:177], v247 offset:18432
	ds_read_b128 v[178:181], v247 offset:19456
	ds_read_b128 v[182:185], v247 offset:20480
	ds_read_b128 v[186:189], v247 offset:21504
	ds_read_b128 v[212:215], v247 offset:22528
	ds_read_b128 v[216:219], v247 offset:23552
	global_load_lds_dwordx4 v[208:209], off
	s_add_i32 m0, s55, 0x2000
	s_add_u32 s56, s22, 0x40000
	v_lshl_add_u64 v[220:221], s[22:23], 0, v[192:193]
	s_addc_u32 s57, s23, 0
	s_add_i32 s55, s58, s10
	global_load_lds_dwordx4 v[220:221], off
	v_lshl_add_u64 v[222:223], s[56:57], 0, v[0:1]
	s_mov_b32 m0, s55
	v_lshl_add_u64 v[224:225], s[40:41], 0, v[190:191]
	global_load_lds_dwordx4 v[222:223], off
	v_lshl_add_u64 v[222:223], s[56:57], 0, v[192:193]
	s_add_i32 m0, s55, 0x2000
	s_nop 0
	global_load_lds_dwordx4 v[222:223], off
	v_lshl_add_u64 v[222:223], s[40:41], 0, v[14:15]
	s_mov_b32 m0, s11
	s_nop 0
	global_load_lds_dwordx4 v[222:223], off
	s_mov_b32 m0, s9
	s_nop 0
	global_load_lds_dwordx4 v[224:225], off
	s_setprio 1
	s_waitcnt vmcnt(8) lgkmcnt(0)
	s_barrier
; #define PG8_STAGE(bufoff, gbase, voff) do { _Pragma("unroll") for (int _i = 0; _i < 2; ++_i) \
;         __builtin_amdgcn_global_load_lds((const unsigned*)((const char*)(gbase) + (voff)[_i]), (LAS unsigned*)(lds + (bufoff) + ldsw + _i * 8192), 16, 0, 0); } while (0)
; #define PG8_LDA(dst, b, h) do { _Pragma("unroll") for (int m = 0; m < 4; ++m) _Pragma("unroll") for (int k = 0; k < 2; ++k) dst[m][k] = *(const LAS bf16x8*)(lds + PG8_SA(b, h) + aoff + m * 2048 + k * 1024); } while (0)
; #define PG8_LDB(dst, b, h) do { _Pragma("unroll") for (int n = 0; n < 2; ++n) _Pragma("unroll") for (int k = 0; k < 2; ++k) dst[n][k] = *(const LAS bf16x8*)(lds + PG8_SB(b, h) + boff + n * 2048 + k * 1024); } while (0)
; #define PG8_MMA(ai, bj, At, Bt) do { __builtin_amdgcn_s_setprio(1); _Pragma("unroll") for (int m = 0; m < 4; ++m) _Pragma("unroll") for (int n = 0; n < 2; ++n) _Pragma("unroll") for (int k = 0; k < 2; ++k) \
;         acc[ai][bj][m][n] = __builtin_amdgcn_mfma_f32_16x16x32_bf16(Bt[n][k], At[m][k], acc[ai][bj][m][n], 0, 0, 0); __builtin_amdgcn_s_setprio(0); } while (0)
; #define PG8_WAIT_V(n) asm volatile("s_waitcnt vmcnt(" #n ")" ::: "memory")
; #define PG8_BAR __builtin_amdgcn_s_barrier()
; template <class Epi, bool SEG>
; __device__ __forceinline__ void gemm_phase(LAS unsigned char* lds, const Gemm g, const int G, const int cidx, const Epi& E) {
;     ...
;             PG8_LDB(B0, 0, 0); PG8_LDB(B1, 0, 1); PG8_SCHED; PG8_LDA(At, 0, 0); PG8_STAGE(PG8_SA(1, 1), a1 + hstepA, voffA);
;             PG8_WAIT_V(8); PG8_WAIT_L(0); PG8_BAR; PG8_MMA(0, 0, At, B0); PG8_MMA(0, 1, At, B1); PG8_BAR; PG8_SCHED;
;             PG8_LDA(At, 0, 1); PG8_STAGE(PG8_SB(0, 0), b2, voffB); PG8_STAGE(PG8_SB(0, 1), b2 + hstepB, voffB); PG8_STAGE(PG8_SA(0, 0), a2, voffA);
;             PG8_WAIT_V(8); PG8_WAIT_L(0); PG8_BAR; PG8_MMA(1, 0, At, B0); PG8_MMA(1, 1, At, B1); PG8_BAR; PG8_SCHED;
;             PG8_LDB(B0, 1, 0); PG8_LDB(B1, 1, 1); PG8_SCHED; PG8_LDA(At, 1, 0); PG8_STAGE(PG8_SA(0, 1), a2 + hstepA, voffA);
;             PG8_WAIT_V(8); PG8_WAIT_L(0); PG8_BAR; PG8_MMA(0, 0, At, B0); PG8_MMA(0, 1, At, B1); PG8_BAR; PG8_SCHED;
;             PG8_LDA(At, 1, 1); PG8_STAGE(PG8_SB(1, 0), b3, voffB); PG8_STAGE(PG8_SB(1, 1), b3 + hstepB, voffB); PG8_STAGE(PG8_SA(1, 0), a3, voffA);
;             PG8_WAIT_V(8); PG8_WAIT_L(0); PG8_BAR; PG8_MMA(1, 0, At, B0); PG8_MMA(1, 1, At, B1); PG8_BAR; PG8_SCHED;
	v_mfma_f32_16x16x32_bf16 v[98:101], v[102:105], v[166:169], v[98:101]
	v_mfma_f32_16x16x32_bf16 v[34:37], v[110:113], v[166:169], v[34:37]
	v_mfma_f32_16x16x32_bf16 v[94:97], v[102:105], v[174:177], v[94:97]
	v_mfma_f32_16x16x32_bf16 v[30:33], v[110:113], v[174:177], v[30:33]
	v_mfma_f32_16x16x32_bf16 v[82:85], v[102:105], v[182:185], v[82:85]
	v_mfma_f32_16x16x32_bf16 v[18:21], v[110:113], v[182:185], v[18:21]
	v_mfma_f32_16x16x32_bf16 v[74:77], v[102:105], v[212:215], v[74:77]
	v_mfma_f32_16x16x32_bf16 v[6:9], v[110:113], v[212:215], v[6:9]
	v_mfma_f32_16x16x32_bf16 v[98:101], v[106:109], v[170:173], v[98:101]
	v_mfma_f32_16x16x32_bf16 v[34:37], v[114:117], v[170:173], v[34:37]
	v_mfma_f32_16x16x32_bf16 v[94:97], v[106:109], v[178:181], v[94:97]
	v_mfma_f32_16x16x32_bf16 v[30:33], v[114:117], v[178:181], v[30:33]
	v_mfma_f32_16x16x32_bf16 v[82:85], v[106:109], v[186:189], v[82:85]
	v_mfma_f32_16x16x32_bf16 v[18:21], v[114:117], v[186:189], v[18:21]
	v_mfma_f32_16x16x32_bf16 v[74:77], v[106:109], v[216:219], v[74:77]
	v_mfma_f32_16x16x32_bf16 v[6:9], v[114:117], v[216:219], v[6:9]
	s_setprio 0
	s_setprio 1
	v_mfma_f32_16x16x32_bf16 v[90:93], v[118:121], v[166:169], v[90:93]
	v_mfma_f32_16x16x32_bf16 v[26:29], v[126:129], v[166:169], v[26:29]
	v_mfma_f32_16x16x32_bf16 v[86:89], v[118:121], v[174:177], v[86:89]
	v_mfma_f32_16x16x32_bf16 v[22:25], v[126:129], v[174:177], v[22:25]
	v_mfma_f32_16x16x32_bf16 v[78:81], v[118:121], v[182:185], v[78:81]
	v_mfma_f32_16x16x32_bf16 v[10:13], v[126:129], v[182:185], v[10:13]
	v_mfma_f32_16x16x32_bf16 v[70:73], v[118:121], v[212:215], v[70:73]
	v_mfma_f32_16x16x32_bf16 v[2:5], v[126:129], v[212:215], v[2:5]
	v_mfma_f32_16x16x32_bf16 v[90:93], v[122:125], v[170:173], v[90:93]
	v_mfma_f32_16x16x32_bf16 v[26:29], v[130:133], v[170:173], v[26:29]
	v_mfma_f32_16x16x32_bf16 v[86:89], v[122:125], v[178:181], v[86:89]
	v_mfma_f32_16x16x32_bf16 v[22:25], v[130:133], v[178:181], v[22:25]
	v_mfma_f32_16x16x32_bf16 v[78:81], v[122:125], v[186:189], v[78:81]
	v_mfma_f32_16x16x32_bf16 v[10:13], v[130:133], v[186:189], v[10:13]
	v_mfma_f32_16x16x32_bf16 v[70:73], v[122:125], v[216:219], v[70:73]
	s_setprio 0
	v_mfma_f32_16x16x32_bf16 v[2:5], v[130:133], v[216:219], v[2:5]
	s_barrier
	s_add_i32 s55, 0, 0x18000
	s_add_i32 s56, 0, 0x1c000
	v_add_u32_e32 v114, s55, v243
	v_add_u32_e32 v130, s56, v243
	ds_read_b128 v[102:105], v114
	ds_read_b128 v[106:109], v114 offset:1024
	ds_read_b128 v[110:113], v114 offset:2048
	ds_read_b128 v[114:117], v114 offset:3072
	ds_read_b128 v[118:121], v130
	ds_read_b128 v[122:125], v130 offset:1024
	ds_read_b128 v[126:129], v130 offset:2048
	ds_read_b128 v[130:133], v130 offset:3072
	s_add_u32 s40, s40, 0x3e000
	s_addc_u32 s41, s41, 0
	s_mov_b32 m0, s36
	v_lshl_add_u64 v[226:227], s[40:41], 0, v[14:15]
	ds_read_b128 v[166:169], v247 offset:32768
	ds_read_b128 v[170:173], v247 offset:33792
	ds_read_b128 v[174:177], v247 offset:34816
	ds_read_b128 v[178:181], v247 offset:35840
	ds_read_b128 v[182:185], v247 offset:36864
	ds_read_b128 v[186:189], v247 offset:37888
	ds_read_b128 v[212:215], v247 offset:38912
	ds_read_b128 v[216:219], v247 offset:39936
	global_load_lds_dwordx4 v[226:227], off
	v_lshl_add_u64 v[226:227], s[40:41], 0, v[190:191]
	s_mov_b32 m0, s12
	s_nop 0
	global_load_lds_dwordx4 v[226:227], off
	s_setprio 1
	s_waitcnt vmcnt(8) lgkmcnt(0)
	s_barrier
	v_mfma_f32_16x16x32_bf16 v[162:165], v[102:105], v[166:169], v[162:165]
	v_mfma_f32_16x16x32_bf16 v[66:69], v[110:113], v[166:169], v[66:69]
	v_mfma_f32_16x16x32_bf16 v[158:161], v[102:105], v[174:177], v[158:161]
	v_mfma_f32_16x16x32_bf16 v[62:65], v[110:113], v[174:177], v[62:65]
	v_mfma_f32_16x16x32_bf16 v[146:149], v[102:105], v[182:185], v[146:149]
	v_mfma_f32_16x16x32_bf16 v[50:53], v[110:113], v[182:185], v[50:53]
	v_mfma_f32_16x16x32_bf16 v[138:141], v[102:105], v[212:215], v[138:141]
	v_mfma_f32_16x16x32_bf16 v[42:45], v[110:113], v[212:215], v[42:45]
	v_mfma_f32_16x16x32_bf16 v[162:165], v[106:109], v[170:173], v[162:165]
	v_mfma_f32_16x16x32_bf16 v[66:69], v[114:117], v[170:173], v[66:69]
	v_mfma_f32_16x16x32_bf16 v[158:161], v[106:109], v[178:181], v[158:161]
	v_mfma_f32_16x16x32_bf16 v[62:65], v[114:117], v[178:181], v[62:65]
	v_mfma_f32_16x16x32_bf16 v[146:149], v[106:109], v[186:189], v[146:149]
	v_mfma_f32_16x16x32_bf16 v[50:53], v[114:117], v[186:189], v[50:53]
	v_mfma_f32_16x16x32_bf16 v[138:141], v[106:109], v[216:219], v[138:141]
	v_mfma_f32_16x16x32_bf16 v[42:45], v[114:117], v[216:219], v[42:45]
	s_setprio 0
	s_setprio 1
	v_mfma_f32_16x16x32_bf16 v[154:157], v[118:121], v[166:169], v[154:157]
	v_mfma_f32_16x16x32_bf16 v[58:61], v[126:129], v[166:169], v[58:61]
	v_mfma_f32_16x16x32_bf16 v[150:153], v[118:121], v[174:177], v[150:153]
	v_mfma_f32_16x16x32_bf16 v[54:57], v[126:129], v[174:177], v[54:57]
	v_mfma_f32_16x16x32_bf16 v[142:145], v[118:121], v[182:185], v[142:145]
	v_mfma_f32_16x16x32_bf16 v[46:49], v[126:129], v[182:185], v[46:49]
	v_mfma_f32_16x16x32_bf16 v[134:137], v[118:121], v[212:215], v[134:137]
	v_mfma_f32_16x16x32_bf16 v[38:41], v[126:129], v[212:215], v[38:41]
	v_mfma_f32_16x16x32_bf16 v[154:157], v[122:125], v[170:173], v[154:157]
	v_mfma_f32_16x16x32_bf16 v[58:61], v[130:133], v[170:173], v[58:61]
	v_mfma_f32_16x16x32_bf16 v[150:153], v[122:125], v[178:181], v[150:153]
	v_mfma_f32_16x16x32_bf16 v[54:57], v[130:133], v[178:181], v[54:57]
	v_mfma_f32_16x16x32_bf16 v[142:145], v[122:125], v[186:189], v[142:145]
	v_mfma_f32_16x16x32_bf16 v[46:49], v[130:133], v[186:189], v[46:49]
	v_mfma_f32_16x16x32_bf16 v[134:137], v[122:125], v[216:219], v[134:137]
	s_setprio 0
	v_mfma_f32_16x16x32_bf16 v[38:41], v[130:133], v[216:219], v[38:41]
	s_barrier
; #define PG8_STAGE(bufoff, gbase, voff) do { _Pragma("unroll") for (int _i = 0; _i < 2; ++_i) \
;         __builtin_amdgcn_global_load_lds((const unsigned*)((const char*)(gbase) + (voff)[_i]), (LAS unsigned*)(lds + (bufoff) + ldsw + _i * 8192), 16, 0, 0); } while (0)
; #define PG8_LDA(dst, b, h) do { _Pragma("unroll") for (int m = 0; m < 4; ++m) _Pragma("unroll") for (int k = 0; k < 2; ++k) dst[m][k] = *(const LAS bf16x8*)(lds + PG8_SA(b, h) + aoff + m * 2048 + k * 1024); } while (0)
; #define PG8_LDB(dst, b, h) do { _Pragma("unroll") for (int n = 0; n < 2; ++n) _Pragma("unroll") for (int k = 0; k < 2; ++k) dst[n][k] = *(const LAS bf16x8*)(lds + PG8_SB(b, h) + boff + n * 2048 + k * 1024); } while (0)
; #define PG8_MMA(ai, bj, At, Bt) do { __builtin_amdgcn_s_setprio(1); _Pragma("unroll") for (int m = 0; m < 4; ++m) _Pragma("unroll") for (int n = 0; n < 2; ++n) _Pragma("unroll") for (int k = 0; k < 2; ++k) \
;         acc[ai][bj][m][n] = __builtin_amdgcn_mfma_f32_16x16x32_bf16(Bt[n][k], At[m][k], acc[ai][bj][m][n], 0, 0, 0); __builtin_amdgcn_s_setprio(0); } while (0)
; #define PG8_WAIT_V(n) asm volatile("s_waitcnt vmcnt(" #n ")" ::: "memory")
; #define PG8_BAR __builtin_amdgcn_s_barrier()
; template <class Epi, bool SEG>
; __device__ __forceinline__ void gemm_phase(LAS unsigned char* lds, const Gemm g, const int G, const int cidx, const Epi& E) {
;     ...
;             PG8_LDB(B0, 0, 0); PG8_LDB(B1, 0, 1); PG8_SCHED; PG8_LDA(At, 0, 0); PG8_STAGE(PG8_SA(1, 1), a1 + hstepA, voffA);
;             PG8_WAIT_V(8); PG8_WAIT_L(0); PG8_BAR; PG8_MMA(0, 0, At, B0); PG8_MMA(0, 1, At, B1); PG8_BAR; PG8_SCHED;
;             PG8_LDA(At, 0, 1); PG8_STAGE(PG8_SB(0, 0), b2, voffB); PG8_STAGE(PG8_SB(0, 1), b2 + hstepB, voffB); PG8_STAGE(PG8_SA(0, 0), a2, voffA);
;             PG8_WAIT_V(8); PG8_WAIT_L(0); PG8_BAR; PG8_MMA(1, 0, At, B0); PG8_MMA(1, 1, At, B1); PG8_BAR; PG8_SCHED;
;             PG8_LDB(B0, 1, 0); PG8_LDB(B1, 1, 1); PG8_SCHED; PG8_LDA(At, 1, 0); PG8_STAGE(PG8_SA(0, 1), a2 + hstepA, voffA);
;             PG8_WAIT_V(8); PG8_WAIT_L(0); PG8_BAR; PG8_MMA(0, 0, At, B0); PG8_MMA(0, 1, At, B1); PG8_BAR; PG8_SCHED;
;             PG8_LDA(At, 1, 1); PG8_STAGE(PG8_SB(1, 0), b3, voffB); PG8_STAGE(PG8_SB(1, 1), b3 + hstepB, voffB); PG8_STAGE(PG8_SA(1, 0), a3, voffA);
;             PG8_WAIT_V(8); PG8_WAIT_L(0); PG8_BAR; PG8_MMA(1, 0, At, B0); PG8_MMA(1, 1, At, B1); PG8_BAR; PG8_SCHED;
	s_add_i32 s40, s55, s10
	v_lshl_add_u64 v[208:209], v[208:209], 0, s[28:29]
	s_mov_b32 m0, s40
	ds_read_b128 v[166:169], v247 offset:49152
	ds_read_b128 v[170:173], v247 offset:50176
	ds_read_b128 v[174:177], v247 offset:51200
	ds_read_b128 v[178:181], v247 offset:52224
	ds_read_b128 v[182:185], v247 offset:53248
	ds_read_b128 v[186:189], v247 offset:54272
	ds_read_b128 v[212:215], v247 offset:55296
	ds_read_b128 v[216:219], v247 offset:56320
	global_load_lds_dwordx4 v[208:209], off
	s_add_i32 m0, s40, 0x2000
	s_add_u32 s22, s22, 0x40080
	v_lshl_add_u64 v[208:209], v[220:221], 0, s[28:29]
	s_addc_u32 s23, s23, 0
	s_add_i32 s40, s56, s10
	global_load_lds_dwordx4 v[208:209], off
	v_lshl_add_u64 v[208:209], s[22:23], 0, v[0:1]
	s_mov_b32 m0, s40
	s_nop 0
	global_load_lds_dwordx4 v[208:209], off
	v_lshl_add_u64 v[208:209], s[22:23], 0, v[192:193]
	s_add_i32 m0, s40, 0x2000
	s_nop 0
	global_load_lds_dwordx4 v[208:209], off
	v_lshl_add_u64 v[208:209], v[222:223], 0, s[28:29]
	s_mov_b32 m0, s13
	s_nop 0
	global_load_lds_dwordx4 v[208:209], off
	v_lshl_add_u64 v[208:209], v[224:225], 0, s[28:29]
	s_mov_b32 m0, s8
	s_nop 0
	global_load_lds_dwordx4 v[208:209], off
	s_setprio 1
	s_waitcnt vmcnt(8) lgkmcnt(0)
	s_barrier
	v_mfma_f32_16x16x32_bf16 v[98:101], v[102:105], v[166:169], v[98:101]
	v_mfma_f32_16x16x32_bf16 v[34:37], v[110:113], v[166:169], v[34:37]
	v_mfma_f32_16x16x32_bf16 v[94:97], v[102:105], v[174:177], v[94:97]
	v_mfma_f32_16x16x32_bf16 v[30:33], v[110:113], v[174:177], v[30:33]
	v_mfma_f32_16x16x32_bf16 v[82:85], v[102:105], v[182:185], v[82:85]
	v_mfma_f32_16x16x32_bf16 v[18:21], v[110:113], v[182:185], v[18:21]
	v_mfma_f32_16x16x32_bf16 v[74:77], v[102:105], v[212:215], v[74:77]
	v_mfma_f32_16x16x32_bf16 v[6:9], v[110:113], v[212:215], v[6:9]
	v_mfma_f32_16x16x32_bf16 v[98:101], v[106:109], v[170:173], v[98:101]
	v_mfma_f32_16x16x32_bf16 v[34:37], v[114:117], v[170:173], v[34:37]
	v_mfma_f32_16x16x32_bf16 v[94:97], v[106:109], v[178:181], v[94:97]
	v_mfma_f32_16x16x32_bf16 v[30:33], v[114:117], v[178:181], v[30:33]
	v_mfma_f32_16x16x32_bf16 v[82:85], v[106:109], v[186:189], v[82:85]
	v_mfma_f32_16x16x32_bf16 v[18:21], v[114:117], v[186:189], v[18:21]
	v_mfma_f32_16x16x32_bf16 v[74:77], v[106:109], v[216:219], v[74:77]
	v_mfma_f32_16x16x32_bf16 v[6:9], v[114:117], v[216:219], v[6:9]
	s_setprio 0
	s_setprio 1
	v_mfma_f32_16x16x32_bf16 v[90:93], v[118:121], v[166:169], v[90:93]
	v_mfma_f32_16x16x32_bf16 v[26:29], v[126:129], v[166:169], v[26:29]
	v_mfma_f32_16x16x32_bf16 v[86:89], v[118:121], v[174:177], v[86:89]
	v_mfma_f32_16x16x32_bf16 v[22:25], v[126:129], v[174:177], v[22:25]
	v_mfma_f32_16x16x32_bf16 v[78:81], v[118:121], v[182:185], v[78:81]
	v_mfma_f32_16x16x32_bf16 v[10:13], v[126:129], v[182:185], v[10:13]
	v_mfma_f32_16x16x32_bf16 v[70:73], v[118:121], v[212:215], v[70:73]
	v_mfma_f32_16x16x32_bf16 v[2:5], v[126:129], v[212:215], v[2:5]
	v_mfma_f32_16x16x32_bf16 v[90:93], v[122:125], v[170:173], v[90:93]
	v_mfma_f32_16x16x32_bf16 v[26:29], v[130:133], v[170:173], v[26:29]
	v_mfma_f32_16x16x32_bf16 v[86:89], v[122:125], v[178:181], v[86:89]
	v_mfma_f32_16x16x32_bf16 v[22:25], v[130:133], v[178:181], v[22:25]
	v_mfma_f32_16x16x32_bf16 v[78:81], v[122:125], v[186:189], v[78:81]
	v_mfma_f32_16x16x32_bf16 v[10:13], v[130:133], v[186:189], v[10:13]
	v_mfma_f32_16x16x32_bf16 v[70:73], v[122:125], v[216:219], v[70:73]
	s_setprio 0
	v_mfma_f32_16x16x32_bf16 v[2:5], v[130:133], v[216:219], v[2:5]
	s_barrier
	s_add_i32 s54, s54, 2
	s_add_u32 s6, s6, 0x100
	s_addc_u32 s7, s7, 0
	s_add_u32 s52, s52, 0x100
	s_addc_u32 s53, s53, 0
	s_cmp_gt_u32 s54, 13
	s_cbranch_scc0 .LBB0_786
	v_readlane_b32 s6, v255, 19
	v_readlane_b32 s7, v255, 20
	s_mov_b64 s[46:47], s[82:83]
	s_and_b64 vcc, exec, s[6:7]
	s_cbranch_vccz .LBB0_789
	s_barrier

; #define PG8_STAGE(bufoff, gbase, voff) do { _Pragma("unroll") for (int _i = 0; _i < 2; ++_i) \
;         __builtin_amdgcn_global_load_lds((const unsigned*)((const char*)(gbase) + (voff)[_i]), (LAS unsigned*)(lds + (bufoff) + ldsw + _i * 8192), 16, 0, 0); } while (0)
; #define PG8_LDA(dst, b, h) do { _Pragma("unroll") for (int m = 0; m < 4; ++m) _Pragma("unroll") for (int k = 0; k < 2; ++k) dst[m][k] = *(const LAS bf16x8*)(lds + PG8_SA(b, h) + aoff + m * 2048 + k * 1024); } while (0)
; #define PG8_LDB(dst, b, h) do { _Pragma("unroll") for (int n = 0; n < 2; ++n) _Pragma("unroll") for (int k = 0; k < 2; ++k) dst[n][k] = *(const LAS bf16x8*)(lds + PG8_SB(b, h) + boff + n * 2048 + k * 1024); } while (0)
; #define PG8_MMA(ai, bj, At, Bt) do { __builtin_amdgcn_s_setprio(1); _Pragma("unroll") for (int m = 0; m < 4; ++m) _Pragma("unroll") for (int n = 0; n < 2; ++n) _Pragma("unroll") for (int k = 0; k < 2; ++k) \
;         acc[ai][bj][m][n] = __builtin_amdgcn_mfma_f32_16x16x32_bf16(Bt[n][k], At[m][k], acc[ai][bj][m][n], 0, 0, 0); __builtin_amdgcn_s_setprio(0); } while (0)
; #define PG8_WAIT_V(n) asm volatile("s_waitcnt vmcnt(" #n ")" ::: "memory")
; #define PG8_BAR __builtin_amdgcn_s_barrier()
; template <class Epi, bool SEG>
; __device__ __forceinline__ void gemm_phase(LAS unsigned char* lds, const Gemm g, const int G, const int cidx, const Epi& E) {
;     ...
;             PG8_LDB(B0, 0, 0); PG8_LDB(B1, 0, 1); PG8_SCHED; PG8_LDA(At, 0, 0); PG8_STAGE(PG8_SA(1, 1), a1 + hstepA, voffA);
;             PG8_WAIT_V(8); PG8_WAIT_L(0); PG8_BAR; PG8_MMA(0, 0, At, B0); PG8_MMA(0, 1, At, B1); PG8_BAR; PG8_SCHED;
;             PG8_LDA(At, 0, 1); PG8_STAGE(PG8_SB(0, 0), b2, voffB); PG8_STAGE(PG8_SB(0, 1), b2 + hstepB, voffB); PG8_STAGE(PG8_SA(0, 0), a2, voffA);
;             PG8_WAIT_V(8); PG8_WAIT_L(0); PG8_BAR; PG8_MMA(1, 0, At, B0); PG8_MMA(1, 1, At, B1); PG8_BAR; PG8_SCHED;
;             PG8_LDB(B0, 1, 0); PG8_LDB(B1, 1, 1); PG8_SCHED; PG8_LDA(At, 1, 0); PG8_STAGE(PG8_SA(0, 1), a2 + hstepA, voffA);
;             PG8_WAIT_V(8); PG8_WAIT_L(0); PG8_BAR; PG8_MMA(0, 0, At, B0); PG8_MMA(0, 1, At, B1); PG8_BAR; PG8_SCHED;
;             PG8_LDA(At, 1, 1); PG8_STAGE(PG8_SB(1, 0), b3, voffB); PG8_STAGE(PG8_SB(1, 1), b3 + hstepB, voffB); PG8_STAGE(PG8_SA(1, 0), a3, voffA);
;             PG8_WAIT_V(8); PG8_WAIT_L(0); PG8_BAR; PG8_MMA(1, 0, At, B0); PG8_MMA(1, 1, At, B1); PG8_BAR; PG8_SCHED;
.LBB0_958:
	s_add_u32 s20, s18, 0x100
	s_addc_u32 s21, s19, 0
	s_add_i32 s55, 0, 0x10000
	s_cmp_eq_u32 s54, 40
	s_cselect_b32 s47, s7, s21
	s_cselect_b32 s46, s6, s20
	s_cselect_b32 s23, s17, s53
	s_cselect_b32 s22, s16, s52
	s_add_i32 s56, 0, 0x14000
	v_add_u32_e32 v146, s55, v228
	v_add_u32_e32 v162, s56, v228
	ds_read_b128 v[130:133], v146
	ds_read_b128 v[138:141], v146 offset:1024
	ds_read_b128 v[142:145], v146 offset:2048
	ds_read_b128 v[146:149], v146 offset:3072
	ds_read_b128 v[150:153], v162
	ds_read_b128 v[154:157], v162 offset:1024
	ds_read_b128 v[158:161], v162 offset:2048
	ds_read_b128 v[162:165], v162 offset:3072
	v_lshl_add_u64 v[208:209], s[18:19], 0, v[198:199]
	s_add_i32 m0, s30, 0xc000
	ds_read_b128 v[166:169], v244
	ds_read_b128 v[170:173], v244 offset:1024
	ds_read_b128 v[174:177], v244 offset:2048
	ds_read_b128 v[178:181], v244 offset:3072
	ds_read_b128 v[182:185], v244 offset:4096
	ds_read_b128 v[186:189], v244 offset:5120
	ds_read_b128 v[190:193], v244 offset:6144
	ds_read_b128 v[212:215], v244 offset:7168
	global_load_lds_dwordx4 v[208:209], off
	v_lshl_add_u64 v[208:209], s[18:19], 0, v[200:201]
	s_add_i32 m0, s30, 0xe000
	s_nop 0
	global_load_lds_dwordx4 v[208:209], off
	s_setprio 1
	s_waitcnt vmcnt(8) lgkmcnt(0)
	s_barrier
	v_mfma_f32_16x16x32_bf16 v[134:137], v[130:133], v[166:169], v[134:137]
	v_mfma_f32_16x16x32_bf16 v[126:129], v[142:145], v[166:169], v[126:129]
	v_mfma_f32_16x16x32_bf16 v[114:117], v[130:133], v[174:177], v[114:117]
	v_mfma_f32_16x16x32_bf16 v[110:113], v[142:145], v[174:177], v[110:113]
	v_mfma_f32_16x16x32_bf16 v[98:101], v[130:133], v[182:185], v[98:101]
	v_mfma_f32_16x16x32_bf16 v[94:97], v[142:145], v[182:185], v[94:97]
	v_mfma_f32_16x16x32_bf16 v[82:85], v[130:133], v[190:193], v[82:85]
	v_mfma_f32_16x16x32_bf16 v[78:81], v[142:145], v[190:193], v[78:81]
	v_mfma_f32_16x16x32_bf16 v[134:137], v[138:141], v[170:173], v[134:137]
	v_mfma_f32_16x16x32_bf16 v[126:129], v[146:149], v[170:173], v[126:129]
	v_mfma_f32_16x16x32_bf16 v[114:117], v[138:141], v[178:181], v[114:117]
	v_mfma_f32_16x16x32_bf16 v[110:113], v[146:149], v[178:181], v[110:113]
	v_mfma_f32_16x16x32_bf16 v[98:101], v[138:141], v[186:189], v[98:101]
	v_mfma_f32_16x16x32_bf16 v[94:97], v[146:149], v[186:189], v[94:97]
	v_mfma_f32_16x16x32_bf16 v[82:85], v[138:141], v[212:215], v[82:85]
	v_mfma_f32_16x16x32_bf16 v[78:81], v[146:149], v[212:215], v[78:81]
	s_setprio 0
	s_setprio 1
	v_mfma_f32_16x16x32_bf16 v[122:125], v[150:153], v[166:169], v[122:125]
	v_mfma_f32_16x16x32_bf16 v[118:121], v[158:161], v[166:169], v[118:121]
	v_mfma_f32_16x16x32_bf16 v[106:109], v[150:153], v[174:177], v[106:109]
	v_mfma_f32_16x16x32_bf16 v[102:105], v[158:161], v[174:177], v[102:105]
	v_mfma_f32_16x16x32_bf16 v[90:93], v[150:153], v[182:185], v[90:93]
	v_mfma_f32_16x16x32_bf16 v[86:89], v[158:161], v[182:185], v[86:89]
	v_mfma_f32_16x16x32_bf16 v[74:77], v[150:153], v[190:193], v[74:77]
	v_mfma_f32_16x16x32_bf16 v[70:73], v[158:161], v[190:193], v[70:73]
	v_mfma_f32_16x16x32_bf16 v[122:125], v[154:157], v[170:173], v[122:125]
	v_mfma_f32_16x16x32_bf16 v[118:121], v[162:165], v[170:173], v[118:121]
	v_mfma_f32_16x16x32_bf16 v[106:109], v[154:157], v[178:181], v[106:109]
	v_mfma_f32_16x16x32_bf16 v[102:105], v[162:165], v[178:181], v[102:105]
	v_mfma_f32_16x16x32_bf16 v[90:93], v[154:157], v[186:189], v[90:93]
	v_mfma_f32_16x16x32_bf16 v[86:89], v[162:165], v[186:189], v[86:89]
	v_mfma_f32_16x16x32_bf16 v[74:77], v[154:157], v[212:215], v[74:77]
	s_setprio 0
	v_mfma_f32_16x16x32_bf16 v[70:73], v[162:165], v[212:215], v[70:73]
	s_barrier
	s_add_i32 s18, s55, s9
	v_lshl_add_u64 v[208:209], s[22:23], 0, v[0:1]
	s_mov_b32 m0, s18
	ds_read_b128 v[166:169], v244 offset:16384
	ds_read_b128 v[170:173], v244 offset:17408
	ds_read_b128 v[174:177], v244 offset:18432
	ds_read_b128 v[178:181], v244 offset:19456
	ds_read_b128 v[182:185], v244 offset:20480
	ds_read_b128 v[186:189], v244 offset:21504
	ds_read_b128 v[190:193], v244 offset:22528
	ds_read_b128 v[212:215], v244 offset:23552
	global_load_lds_dwordx4 v[208:209], off
	s_add_i32 m0, s18, 0x2000
	s_add_u32 s18, s22, 0xb0000
	v_lshl_add_u64 v[216:217], s[22:23], 0, v[14:15]
	s_addc_u32 s19, s23, 0
	s_add_i32 s55, s56, s9
	global_load_lds_dwordx4 v[216:217], off
	v_lshl_add_u64 v[218:219], s[18:19], 0, v[0:1]
	s_mov_b32 m0, s55
	v_lshl_add_u64 v[220:221], s[46:47], 0, v[194:195]
	global_load_lds_dwordx4 v[218:219], off
	v_lshl_add_u64 v[218:219], s[18:19], 0, v[14:15]
	s_add_i32 m0, s55, 0x2000
	s_nop 0
	global_load_lds_dwordx4 v[218:219], off
	v_lshl_add_u64 v[218:219], s[46:47], 0, v[196:197]
	s_mov_b32 m0, s30
	s_nop 0
	global_load_lds_dwordx4 v[218:219], off
	s_mov_b32 m0, s31
	s_nop 0
	global_load_lds_dwordx4 v[220:221], off
	s_setprio 1
	s_waitcnt vmcnt(8) lgkmcnt(0)
	s_barrier
; #define PG8_STAGE(bufoff, gbase, voff) do { _Pragma("unroll") for (int _i = 0; _i < 2; ++_i) \
;         __builtin_amdgcn_global_load_lds((const unsigned*)((const char*)(gbase) + (voff)[_i]), (LAS unsigned*)(lds + (bufoff) + ldsw + _i * 8192), 16, 0, 0); } while (0)
; #define PG8_LDA(dst, b, h) do { _Pragma("unroll") for (int m = 0; m < 4; ++m) _Pragma("unroll") for (int k = 0; k < 2; ++k) dst[m][k] = *(const LAS bf16x8*)(lds + PG8_SA(b, h) + aoff + m * 2048 + k * 1024); } while (0)
; #define PG8_LDB(dst, b, h) do { _Pragma("unroll") for (int n = 0; n < 2; ++n) _Pragma("unroll") for (int k = 0; k < 2; ++k) dst[n][k] = *(const LAS bf16x8*)(lds + PG8_SB(b, h) + boff + n * 2048 + k * 1024); } while (0)
; #define PG8_MMA(ai, bj, At, Bt) do { __builtin_amdgcn_s_setprio(1); _Pragma("unroll") for (int m = 0; m < 4; ++m) _Pragma("unroll") for (int n = 0; n < 2; ++n) _Pragma("unroll") for (int k = 0; k < 2; ++k) \
;         acc[ai][bj][m][n] = __builtin_amdgcn_mfma_f32_16x16x32_bf16(Bt[n][k], At[m][k], acc[ai][bj][m][n], 0, 0, 0); __builtin_amdgcn_s_setprio(0); } while (0)
; #define PG8_WAIT_V(n) asm volatile("s_waitcnt vmcnt(" #n ")" ::: "memory")
; #define PG8_BAR __builtin_amdgcn_s_barrier()
; template <class Epi, bool SEG>
; __device__ __forceinline__ void gemm_phase(LAS unsigned char* lds, const Gemm g, const int G, const int cidx, const Epi& E) {
;     ...
;             PG8_LDB(B0, 0, 0); PG8_LDB(B1, 0, 1); PG8_SCHED; PG8_LDA(At, 0, 0); PG8_STAGE(PG8_SA(1, 1), a1 + hstepA, voffA);
;             PG8_WAIT_V(8); PG8_WAIT_L(0); PG8_BAR; PG8_MMA(0, 0, At, B0); PG8_MMA(0, 1, At, B1); PG8_BAR; PG8_SCHED;
;             PG8_LDA(At, 0, 1); PG8_STAGE(PG8_SB(0, 0), b2, voffB); PG8_STAGE(PG8_SB(0, 1), b2 + hstepB, voffB); PG8_STAGE(PG8_SA(0, 0), a2, voffA);
;             PG8_WAIT_V(8); PG8_WAIT_L(0); PG8_BAR; PG8_MMA(1, 0, At, B0); PG8_MMA(1, 1, At, B1); PG8_BAR; PG8_SCHED;
;             PG8_LDB(B0, 1, 0); PG8_LDB(B1, 1, 1); PG8_SCHED; PG8_LDA(At, 1, 0); PG8_STAGE(PG8_SA(0, 1), a2 + hstepA, voffA);
;             PG8_WAIT_V(8); PG8_WAIT_L(0); PG8_BAR; PG8_MMA(0, 0, At, B0); PG8_MMA(0, 1, At, B1); PG8_BAR; PG8_SCHED;
;             PG8_LDA(At, 1, 1); PG8_STAGE(PG8_SB(1, 0), b3, voffB); PG8_STAGE(PG8_SB(1, 1), b3 + hstepB, voffB); PG8_STAGE(PG8_SA(1, 0), a3, voffA);
;             PG8_WAIT_V(8); PG8_WAIT_L(0); PG8_BAR; PG8_MMA(1, 0, At, B0); PG8_MMA(1, 1, At, B1); PG8_BAR; PG8_SCHED;
	v_mfma_f32_16x16x32_bf16 v[66:69], v[130:133], v[166:169], v[66:69]
	v_mfma_f32_16x16x32_bf16 v[62:65], v[142:145], v[166:169], v[62:65]
	v_mfma_f32_16x16x32_bf16 v[50:53], v[130:133], v[174:177], v[50:53]
	v_mfma_f32_16x16x32_bf16 v[46:49], v[142:145], v[174:177], v[46:49]
	v_mfma_f32_16x16x32_bf16 v[34:37], v[130:133], v[182:185], v[34:37]
	v_mfma_f32_16x16x32_bf16 v[30:33], v[142:145], v[182:185], v[30:33]
	v_mfma_f32_16x16x32_bf16 v[18:21], v[130:133], v[190:193], v[18:21]
	v_mfma_f32_16x16x32_bf16 v[10:13], v[142:145], v[190:193], v[10:13]
	v_mfma_f32_16x16x32_bf16 v[66:69], v[138:141], v[170:173], v[66:69]
	v_mfma_f32_16x16x32_bf16 v[62:65], v[146:149], v[170:173], v[62:65]
	v_mfma_f32_16x16x32_bf16 v[50:53], v[138:141], v[178:181], v[50:53]
	v_mfma_f32_16x16x32_bf16 v[46:49], v[146:149], v[178:181], v[46:49]
	v_mfma_f32_16x16x32_bf16 v[34:37], v[138:141], v[186:189], v[34:37]
	v_mfma_f32_16x16x32_bf16 v[30:33], v[146:149], v[186:189], v[30:33]
	v_mfma_f32_16x16x32_bf16 v[18:21], v[138:141], v[212:215], v[18:21]
	v_mfma_f32_16x16x32_bf16 v[10:13], v[146:149], v[212:215], v[10:13]
	s_setprio 0
	s_setprio 1
	v_mfma_f32_16x16x32_bf16 v[58:61], v[150:153], v[166:169], v[58:61]
	v_mfma_f32_16x16x32_bf16 v[54:57], v[158:161], v[166:169], v[54:57]
	v_mfma_f32_16x16x32_bf16 v[42:45], v[150:153], v[174:177], v[42:45]
	v_mfma_f32_16x16x32_bf16 v[38:41], v[158:161], v[174:177], v[38:41]
	v_mfma_f32_16x16x32_bf16 v[26:29], v[150:153], v[182:185], v[26:29]
	v_mfma_f32_16x16x32_bf16 v[22:25], v[158:161], v[182:185], v[22:25]
	v_mfma_f32_16x16x32_bf16 v[6:9], v[150:153], v[190:193], v[6:9]
	v_mfma_f32_16x16x32_bf16 v[2:5], v[158:161], v[190:193], v[2:5]
	v_mfma_f32_16x16x32_bf16 v[58:61], v[154:157], v[170:173], v[58:61]
	v_mfma_f32_16x16x32_bf16 v[54:57], v[162:165], v[170:173], v[54:57]
	v_mfma_f32_16x16x32_bf16 v[42:45], v[154:157], v[178:181], v[42:45]
	v_mfma_f32_16x16x32_bf16 v[38:41], v[162:165], v[178:181], v[38:41]
	v_mfma_f32_16x16x32_bf16 v[26:29], v[154:157], v[186:189], v[26:29]
	v_mfma_f32_16x16x32_bf16 v[22:25], v[162:165], v[186:189], v[22:25]
	v_mfma_f32_16x16x32_bf16 v[6:9], v[154:157], v[212:215], v[6:9]
	s_setprio 0
	v_mfma_f32_16x16x32_bf16 v[2:5], v[162:165], v[212:215], v[2:5]
	s_barrier
	s_add_i32 s55, 0, 0x18000
	s_add_i32 s56, 0, 0x1c000
	v_add_u32_e32 v146, s55, v228
	v_add_u32_e32 v162, s56, v228
	ds_read_b128 v[130:133], v146
	ds_read_b128 v[138:141], v146 offset:1024
	ds_read_b128 v[142:145], v146 offset:2048
	ds_read_b128 v[146:149], v146 offset:3072
	ds_read_b128 v[150:153], v162
	ds_read_b128 v[154:157], v162 offset:1024
	ds_read_b128 v[158:161], v162 offset:2048
	ds_read_b128 v[162:165], v162 offset:3072
	s_add_u32 s18, s46, 0xb0000
	s_addc_u32 s19, s47, 0
	s_mov_b32 m0, s36
	v_lshl_add_u64 v[222:223], s[18:19], 0, v[196:197]
	ds_read_b128 v[166:169], v244 offset:32768
	ds_read_b128 v[170:173], v244 offset:33792
	ds_read_b128 v[174:177], v244 offset:34816
	ds_read_b128 v[178:181], v244 offset:35840
	ds_read_b128 v[182:185], v244 offset:36864
	ds_read_b128 v[186:189], v244 offset:37888
	ds_read_b128 v[190:193], v244 offset:38912
	ds_read_b128 v[212:215], v244 offset:39936
	global_load_lds_dwordx4 v[222:223], off
	v_lshl_add_u64 v[222:223], s[18:19], 0, v[194:195]
	s_mov_b32 m0, s38
	s_nop 0
	global_load_lds_dwordx4 v[222:223], off
	s_setprio 1
	s_waitcnt vmcnt(8) lgkmcnt(0)
	s_barrier
	v_mfma_f32_16x16x32_bf16 v[134:137], v[130:133], v[166:169], v[134:137]
	v_mfma_f32_16x16x32_bf16 v[126:129], v[142:145], v[166:169], v[126:129]
	v_mfma_f32_16x16x32_bf16 v[114:117], v[130:133], v[174:177], v[114:117]
	v_mfma_f32_16x16x32_bf16 v[110:113], v[142:145], v[174:177], v[110:113]
	v_mfma_f32_16x16x32_bf16 v[98:101], v[130:133], v[182:185], v[98:101]
	v_mfma_f32_16x16x32_bf16 v[94:97], v[142:145], v[182:185], v[94:97]
	v_mfma_f32_16x16x32_bf16 v[82:85], v[130:133], v[190:193], v[82:85]
	v_mfma_f32_16x16x32_bf16 v[78:81], v[142:145], v[190:193], v[78:81]
	v_mfma_f32_16x16x32_bf16 v[134:137], v[138:141], v[170:173], v[134:137]
	v_mfma_f32_16x16x32_bf16 v[126:129], v[146:149], v[170:173], v[126:129]
	v_mfma_f32_16x16x32_bf16 v[114:117], v[138:141], v[178:181], v[114:117]
	v_mfma_f32_16x16x32_bf16 v[110:113], v[146:149], v[178:181], v[110:113]
	v_mfma_f32_16x16x32_bf16 v[98:101], v[138:141], v[186:189], v[98:101]
	v_mfma_f32_16x16x32_bf16 v[94:97], v[146:149], v[186:189], v[94:97]
	v_mfma_f32_16x16x32_bf16 v[82:85], v[138:141], v[212:215], v[82:85]
	v_mfma_f32_16x16x32_bf16 v[78:81], v[146:149], v[212:215], v[78:81]
	s_setprio 0
	s_setprio 1
	v_mfma_f32_16x16x32_bf16 v[122:125], v[150:153], v[166:169], v[122:125]
	v_mfma_f32_16x16x32_bf16 v[118:121], v[158:161], v[166:169], v[118:121]
	v_mfma_f32_16x16x32_bf16 v[106:109], v[150:153], v[174:177], v[106:109]
	v_mfma_f32_16x16x32_bf16 v[102:105], v[158:161], v[174:177], v[102:105]
	v_mfma_f32_16x16x32_bf16 v[90:93], v[150:153], v[182:185], v[90:93]
	v_mfma_f32_16x16x32_bf16 v[86:89], v[158:161], v[182:185], v[86:89]
	v_mfma_f32_16x16x32_bf16 v[74:77], v[150:153], v[190:193], v[74:77]
	v_mfma_f32_16x16x32_bf16 v[70:73], v[158:161], v[190:193], v[70:73]
	v_mfma_f32_16x16x32_bf16 v[122:125], v[154:157], v[170:173], v[122:125]
	v_mfma_f32_16x16x32_bf16 v[118:121], v[162:165], v[170:173], v[118:121]
	v_mfma_f32_16x16x32_bf16 v[106:109], v[154:157], v[178:181], v[106:109]
	v_mfma_f32_16x16x32_bf16 v[102:105], v[162:165], v[178:181], v[102:105]
	v_mfma_f32_16x16x32_bf16 v[90:93], v[154:157], v[186:189], v[90:93]
	v_mfma_f32_16x16x32_bf16 v[86:89], v[162:165], v[186:189], v[86:89]
	v_mfma_f32_16x16x32_bf16 v[74:77], v[154:157], v[212:215], v[74:77]
	s_setprio 0
	v_mfma_f32_16x16x32_bf16 v[70:73], v[162:165], v[212:215], v[70:73]
	s_barrier
; #define PG8_STAGE(bufoff, gbase, voff) do { _Pragma("unroll") for (int _i = 0; _i < 2; ++_i) \
;         __builtin_amdgcn_global_load_lds((const unsigned*)((const char*)(gbase) + (voff)[_i]), (LAS unsigned*)(lds + (bufoff) + ldsw + _i * 8192), 16, 0, 0); } while (0)
; #define PG8_LDA(dst, b, h) do { _Pragma("unroll") for (int m = 0; m < 4; ++m) _Pragma("unroll") for (int k = 0; k < 2; ++k) dst[m][k] = *(const LAS bf16x8*)(lds + PG8_SA(b, h) + aoff + m * 2048 + k * 1024); } while (0)
; #define PG8_LDB(dst, b, h) do { _Pragma("unroll") for (int n = 0; n < 2; ++n) _Pragma("unroll") for (int k = 0; k < 2; ++k) dst[n][k] = *(const LAS bf16x8*)(lds + PG8_SB(b, h) + boff + n * 2048 + k * 1024); } while (0)
; #define PG8_MMA(ai, bj, At, Bt) do { __builtin_amdgcn_s_setprio(1); _Pragma("unroll") for (int m = 0; m < 4; ++m) _Pragma("unroll") for (int n = 0; n < 2; ++n) _Pragma("unroll") for (int k = 0; k < 2; ++k) \
;         acc[ai][bj][m][n] = __builtin_amdgcn_mfma_f32_16x16x32_bf16(Bt[n][k], At[m][k], acc[ai][bj][m][n], 0, 0, 0); __builtin_amdgcn_s_setprio(0); } while (0)
; #define PG8_WAIT_V(n) asm volatile("s_waitcnt vmcnt(" #n ")" ::: "memory")
; #define PG8_BAR __builtin_amdgcn_s_barrier()
; template <class Epi, bool SEG>
; __device__ __forceinline__ void gemm_phase(LAS unsigned char* lds, const Gemm g, const int G, const int cidx, const Epi& E) {
;     ...
;             PG8_LDB(B0, 0, 0); PG8_LDB(B1, 0, 1); PG8_SCHED; PG8_LDA(At, 0, 0); PG8_STAGE(PG8_SA(1, 1), a1 + hstepA, voffA);
;             PG8_WAIT_V(8); PG8_WAIT_L(0); PG8_BAR; PG8_MMA(0, 0, At, B0); PG8_MMA(0, 1, At, B1); PG8_BAR; PG8_SCHED;
;             PG8_LDA(At, 0, 1); PG8_STAGE(PG8_SB(0, 0), b2, voffB); PG8_STAGE(PG8_SB(0, 1), b2 + hstepB, voffB); PG8_STAGE(PG8_SA(0, 0), a2, voffA);
;             PG8_WAIT_V(8); PG8_WAIT_L(0); PG8_BAR; PG8_MMA(1, 0, At, B0); PG8_MMA(1, 1, At, B1); PG8_BAR; PG8_SCHED;
;             PG8_LDB(B0, 1, 0); PG8_LDB(B1, 1, 1); PG8_SCHED; PG8_LDA(At, 1, 0); PG8_STAGE(PG8_SA(0, 1), a2 + hstepA, voffA);
;             PG8_WAIT_V(8); PG8_WAIT_L(0); PG8_BAR; PG8_MMA(0, 0, At, B0); PG8_MMA(0, 1, At, B1); PG8_BAR; PG8_SCHED;
;             PG8_LDA(At, 1, 1); PG8_STAGE(PG8_SB(1, 0), b3, voffB); PG8_STAGE(PG8_SB(1, 1), b3 + hstepB, voffB); PG8_STAGE(PG8_SA(1, 0), a3, voffA);
;             PG8_WAIT_V(8); PG8_WAIT_L(0); PG8_BAR; PG8_MMA(1, 0, At, B0); PG8_MMA(1, 1, At, B1); PG8_BAR; PG8_SCHED;
	s_add_i32 s18, s55, s9
	v_lshl_add_u64 v[208:209], v[208:209], 0, s[28:29]
	s_mov_b32 m0, s18
	ds_read_b128 v[166:169], v244 offset:49152
	ds_read_b128 v[170:173], v244 offset:50176
	ds_read_b128 v[174:177], v244 offset:51200
	ds_read_b128 v[178:181], v244 offset:52224
	ds_read_b128 v[182:185], v244 offset:53248
	ds_read_b128 v[186:189], v244 offset:54272
	ds_read_b128 v[190:193], v244 offset:55296
	ds_read_b128 v[212:215], v244 offset:56320
	global_load_lds_dwordx4 v[208:209], off
	s_add_i32 m0, s18, 0x2000
	s_add_u32 s18, s22, 0xb0080
	v_lshl_add_u64 v[208:209], v[216:217], 0, s[28:29]
	s_addc_u32 s19, s23, 0
	s_add_i32 s22, s56, s9
	global_load_lds_dwordx4 v[208:209], off
	v_lshl_add_u64 v[208:209], s[18:19], 0, v[0:1]
	s_mov_b32 m0, s22
	s_nop 0
	global_load_lds_dwordx4 v[208:209], off
	v_lshl_add_u64 v[208:209], s[18:19], 0, v[14:15]
	s_add_i32 m0, s22, 0x2000
	s_nop 0
	global_load_lds_dwordx4 v[208:209], off
	v_lshl_add_u64 v[208:209], v[218:219], 0, s[28:29]
	s_mov_b32 m0, s39
	s_nop 0
	global_load_lds_dwordx4 v[208:209], off
	v_lshl_add_u64 v[208:209], v[220:221], 0, s[28:29]
	s_mov_b32 m0, s48
	s_nop 0
	global_load_lds_dwordx4 v[208:209], off
	s_setprio 1
	s_waitcnt vmcnt(8) lgkmcnt(0)
	s_barrier
	v_mfma_f32_16x16x32_bf16 v[66:69], v[130:133], v[166:169], v[66:69]
	v_mfma_f32_16x16x32_bf16 v[62:65], v[142:145], v[166:169], v[62:65]
	v_mfma_f32_16x16x32_bf16 v[50:53], v[130:133], v[174:177], v[50:53]
	v_mfma_f32_16x16x32_bf16 v[46:49], v[142:145], v[174:177], v[46:49]
	v_mfma_f32_16x16x32_bf16 v[34:37], v[130:133], v[182:185], v[34:37]
	v_mfma_f32_16x16x32_bf16 v[30:33], v[142:145], v[182:185], v[30:33]
	v_mfma_f32_16x16x32_bf16 v[18:21], v[130:133], v[190:193], v[18:21]
	v_mfma_f32_16x16x32_bf16 v[10:13], v[142:145], v[190:193], v[10:13]
	v_mfma_f32_16x16x32_bf16 v[66:69], v[138:141], v[170:173], v[66:69]
	v_mfma_f32_16x16x32_bf16 v[62:65], v[146:149], v[170:173], v[62:65]
	v_mfma_f32_16x16x32_bf16 v[50:53], v[138:141], v[178:181], v[50:53]
	v_mfma_f32_16x16x32_bf16 v[46:49], v[146:149], v[178:181], v[46:49]
	v_mfma_f32_16x16x32_bf16 v[34:37], v[138:141], v[186:189], v[34:37]
	v_mfma_f32_16x16x32_bf16 v[30:33], v[146:149], v[186:189], v[30:33]
	v_mfma_f32_16x16x32_bf16 v[18:21], v[138:141], v[212:215], v[18:21]
	v_mfma_f32_16x16x32_bf16 v[10:13], v[146:149], v[212:215], v[10:13]
	s_setprio 0
	s_setprio 1
	v_mfma_f32_16x16x32_bf16 v[58:61], v[150:153], v[166:169], v[58:61]
	v_mfma_f32_16x16x32_bf16 v[54:57], v[158:161], v[166:169], v[54:57]
	v_mfma_f32_16x16x32_bf16 v[42:45], v[150:153], v[174:177], v[42:45]
	v_mfma_f32_16x16x32_bf16 v[38:41], v[158:161], v[174:177], v[38:41]
	v_mfma_f32_16x16x32_bf16 v[26:29], v[150:153], v[182:185], v[26:29]
	v_mfma_f32_16x16x32_bf16 v[22:25], v[158:161], v[182:185], v[22:25]
	v_mfma_f32_16x16x32_bf16 v[6:9], v[150:153], v[190:193], v[6:9]
	v_mfma_f32_16x16x32_bf16 v[2:5], v[158:161], v[190:193], v[2:5]
	v_mfma_f32_16x16x32_bf16 v[58:61], v[154:157], v[170:173], v[58:61]
	v_mfma_f32_16x16x32_bf16 v[54:57], v[162:165], v[170:173], v[54:57]
	v_mfma_f32_16x16x32_bf16 v[42:45], v[154:157], v[178:181], v[42:45]
	v_mfma_f32_16x16x32_bf16 v[38:41], v[162:165], v[178:181], v[38:41]
	v_mfma_f32_16x16x32_bf16 v[26:29], v[154:157], v[186:189], v[26:29]
	v_mfma_f32_16x16x32_bf16 v[22:25], v[162:165], v[186:189], v[22:25]
	v_mfma_f32_16x16x32_bf16 v[6:9], v[154:157], v[212:215], v[6:9]
	s_setprio 0
	v_mfma_f32_16x16x32_bf16 v[2:5], v[162:165], v[212:215], v[2:5]
	s_barrier
	s_add_i32 s54, s54, 2
	s_add_u32 s52, s52, 0x100
	s_addc_u32 s53, s53, 0
	s_cmp_gt_u32 s54, 41
	s_mov_b64 s[18:19], s[20:21]
	s_cbranch_scc0 .LBB0_958
	s_and_b64 vcc, exec, s[12:13]
	s_cbranch_vccz .LBB0_961
	s_barrier

; #define PG8_STAGE(bufoff, gbase, voff) do { _Pragma("unroll") for (int _i = 0; _i < 2; ++_i) \
;         __builtin_amdgcn_global_load_lds((const unsigned*)((const char*)(gbase) + (voff)[_i]), (LAS unsigned*)(lds + (bufoff) + ldsw + _i * 8192), 16, 0, 0); } while (0)
; #define PG8_LDA(dst, b, h) do { _Pragma("unroll") for (int m = 0; m < 4; ++m) _Pragma("unroll") for (int k = 0; k < 2; ++k) dst[m][k] = *(const LAS bf16x8*)(lds + PG8_SA(b, h) + aoff + m * 2048 + k * 1024); } while (0)
; #define PG8_LDB(dst, b, h) do { _Pragma("unroll") for (int n = 0; n < 2; ++n) _Pragma("unroll") for (int k = 0; k < 2; ++k) dst[n][k] = *(const LAS bf16x8*)(lds + PG8_SB(b, h) + boff + n * 2048 + k * 1024); } while (0)
; #define PG8_MMA(ai, bj, At, Bt) do { __builtin_amdgcn_s_setprio(1); _Pragma("unroll") for (int m = 0; m < 4; ++m) _Pragma("unroll") for (int n = 0; n < 2; ++n) _Pragma("unroll") for (int k = 0; k < 2; ++k) \
;         acc[ai][bj][m][n] = __builtin_amdgcn_mfma_f32_16x16x32_bf16(Bt[n][k], At[m][k], acc[ai][bj][m][n], 0, 0, 0); __builtin_amdgcn_s_setprio(0); } while (0)
; #define PG8_WAIT_V(n) asm volatile("s_waitcnt vmcnt(" #n ")" ::: "memory")
; #define PG8_BAR __builtin_amdgcn_s_barrier()
; template <class Epi, bool SEG>
; __device__ __forceinline__ void gemm_phase(LAS unsigned char* lds, const Gemm g, const int G, const int cidx, const Epi& E) {
;     ...
;             PG8_LDB(B0, 0, 0); PG8_LDB(B1, 0, 1); PG8_SCHED; PG8_LDA(At, 0, 0); PG8_STAGE(PG8_SA(1, 1), a1 + hstepA, voffA);
;             PG8_WAIT_V(8); PG8_WAIT_L(0); PG8_BAR; PG8_MMA(0, 0, At, B0); PG8_MMA(0, 1, At, B1); PG8_BAR; PG8_SCHED;
;             PG8_LDA(At, 0, 1); PG8_STAGE(PG8_SB(0, 0), b2, voffB); PG8_STAGE(PG8_SB(0, 1), b2 + hstepB, voffB); PG8_STAGE(PG8_SA(0, 0), a2, voffA);
;             PG8_WAIT_V(8); PG8_WAIT_L(0); PG8_BAR; PG8_MMA(1, 0, At, B0); PG8_MMA(1, 1, At, B1); PG8_BAR; PG8_SCHED;
;             PG8_LDB(B0, 1, 0); PG8_LDB(B1, 1, 1); PG8_SCHED; PG8_LDA(At, 1, 0); PG8_STAGE(PG8_SA(0, 1), a2 + hstepA, voffA);
;             PG8_WAIT_V(8); PG8_WAIT_L(0); PG8_BAR; PG8_MMA(0, 0, At, B0); PG8_MMA(0, 1, At, B1); PG8_BAR; PG8_SCHED;
;             PG8_LDA(At, 1, 1); PG8_STAGE(PG8_SB(1, 0), b3, voffB); PG8_STAGE(PG8_SB(1, 1), b3 + hstepB, voffB); PG8_STAGE(PG8_SA(1, 0), a3, voffA);
;             PG8_WAIT_V(8); PG8_WAIT_L(0); PG8_BAR; PG8_MMA(1, 0, At, B0); PG8_MMA(1, 1, At, B1); PG8_BAR; PG8_SCHED;
.LBB0_1060:
	s_add_i32 s63, s42, 2
	s_add_u32 s40, s22, 0x100
	s_addc_u32 s41, s23, 0
	s_add_i32 s66, 0, 0x10000
	s_cmp_eq_u32 s57, s42
	s_cselect_b32 s43, s19, s41
	s_cselect_b32 s42, s18, s40
	v_add_u32_e32 v145, s66, v142
	s_cselect_b32 s65, s21, s62
	s_cselect_b32 s64, s20, s61
	s_add_i32 s67, 0, 0x14000
	ds_read_b128 v[146:149], v145
	ds_read_b128 v[150:153], v145 offset:1024
	ds_read_b128 v[154:157], v145 offset:2048
	ds_read_b128 v[158:161], v145 offset:3072
	v_add_u32_e32 v145, s67, v142
	ds_read_b128 v[162:165], v145
	ds_read_b128 v[166:169], v145 offset:1024
	ds_read_b128 v[170:173], v145 offset:2048
	ds_read_b128 v[174:177], v145 offset:3072
	v_lshl_add_u64 v[220:221], s[22:23], 0, v[138:139]
	s_add_i32 m0, s47, 0xc000
	ds_read_b128 v[178:181], v144
	ds_read_b128 v[182:185], v144 offset:1024
	ds_read_b128 v[186:189], v144 offset:2048
	ds_read_b128 v[190:193], v144 offset:3072
	ds_read_b128 v[194:197], v144 offset:4096
	ds_read_b128 v[198:201], v144 offset:5120
	ds_read_b128 v[212:215], v144 offset:6144
	ds_read_b128 v[216:219], v144 offset:7168
	global_load_lds_dwordx4 v[220:221], off
	v_lshl_add_u64 v[220:221], s[22:23], 0, v[140:141]
	s_add_i32 m0, s47, 0xe000
	s_nop 0
	global_load_lds_dwordx4 v[220:221], off
	s_setprio 1
	s_waitcnt vmcnt(8) lgkmcnt(0)
	s_barrier
	v_mfma_f32_16x16x32_bf16 v[130:133], v[146:149], v[178:181], v[130:133]
	v_mfma_f32_16x16x32_bf16 v[126:129], v[154:157], v[178:181], v[126:129]
	v_mfma_f32_16x16x32_bf16 v[122:125], v[146:149], v[186:189], v[122:125]
	v_mfma_f32_16x16x32_bf16 v[118:121], v[154:157], v[186:189], v[118:121]
	v_mfma_f32_16x16x32_bf16 v[106:109], v[146:149], v[194:197], v[106:109]
	v_mfma_f32_16x16x32_bf16 v[102:105], v[154:157], v[194:197], v[102:105]
	v_mfma_f32_16x16x32_bf16 v[90:93], v[146:149], v[212:215], v[90:93]
	v_mfma_f32_16x16x32_bf16 v[86:89], v[154:157], v[212:215], v[86:89]
	v_mfma_f32_16x16x32_bf16 v[130:133], v[150:153], v[182:185], v[130:133]
	v_mfma_f32_16x16x32_bf16 v[126:129], v[158:161], v[182:185], v[126:129]
	v_mfma_f32_16x16x32_bf16 v[122:125], v[150:153], v[190:193], v[122:125]
	v_mfma_f32_16x16x32_bf16 v[118:121], v[158:161], v[190:193], v[118:121]
	v_mfma_f32_16x16x32_bf16 v[106:109], v[150:153], v[198:201], v[106:109]
	v_mfma_f32_16x16x32_bf16 v[102:105], v[158:161], v[198:201], v[102:105]
	v_mfma_f32_16x16x32_bf16 v[90:93], v[150:153], v[216:219], v[90:93]
	v_mfma_f32_16x16x32_bf16 v[86:89], v[158:161], v[216:219], v[86:89]
	s_setprio 0
	s_setprio 1
	v_mfma_f32_16x16x32_bf16 v[114:117], v[162:165], v[178:181], v[114:117]
	v_mfma_f32_16x16x32_bf16 v[110:113], v[170:173], v[178:181], v[110:113]
	v_mfma_f32_16x16x32_bf16 v[98:101], v[162:165], v[186:189], v[98:101]
	v_mfma_f32_16x16x32_bf16 v[94:97], v[170:173], v[186:189], v[94:97]
	v_mfma_f32_16x16x32_bf16 v[82:85], v[162:165], v[194:197], v[82:85]
	v_mfma_f32_16x16x32_bf16 v[78:81], v[170:173], v[194:197], v[78:81]
	v_mfma_f32_16x16x32_bf16 v[74:77], v[162:165], v[212:215], v[74:77]
	v_mfma_f32_16x16x32_bf16 v[70:73], v[170:173], v[212:215], v[70:73]
	v_mfma_f32_16x16x32_bf16 v[114:117], v[166:169], v[182:185], v[114:117]
	v_mfma_f32_16x16x32_bf16 v[110:113], v[174:177], v[182:185], v[110:113]
	v_mfma_f32_16x16x32_bf16 v[98:101], v[166:169], v[190:193], v[98:101]
	v_mfma_f32_16x16x32_bf16 v[94:97], v[174:177], v[190:193], v[94:97]
	v_mfma_f32_16x16x32_bf16 v[82:85], v[166:169], v[198:201], v[82:85]
	v_mfma_f32_16x16x32_bf16 v[78:81], v[174:177], v[198:201], v[78:81]
	v_mfma_f32_16x16x32_bf16 v[74:77], v[166:169], v[216:219], v[74:77]
	s_setprio 0
	v_mfma_f32_16x16x32_bf16 v[70:73], v[174:177], v[216:219], v[70:73]
	s_barrier
	s_add_i32 s22, s66, s39
	v_lshl_add_u64 v[220:221], s[64:65], 0, v[0:1]
	s_mov_b32 m0, s22
	ds_read_b128 v[178:181], v144 offset:16384
	ds_read_b128 v[182:185], v144 offset:17408
	ds_read_b128 v[186:189], v144 offset:18432
	ds_read_b128 v[190:193], v144 offset:19456
	ds_read_b128 v[194:197], v144 offset:20480
	ds_read_b128 v[198:201], v144 offset:21504
	ds_read_b128 v[212:215], v144 offset:22528
	ds_read_b128 v[216:219], v144 offset:23552
	global_load_lds_dwordx4 v[220:221], off
	s_add_i32 m0, s22, 0x2000
	s_add_u32 s22, s64, s31
	v_lshl_add_u64 v[222:223], s[64:65], 0, v[14:15]
	s_addc_u32 s23, s65, 0
	s_add_i32 s64, s67, s39
	global_load_lds_dwordx4 v[222:223], off
	v_lshl_add_u64 v[224:225], s[22:23], 0, v[0:1]
	s_mov_b32 m0, s64
	v_lshl_add_u64 v[226:227], s[22:23], 0, v[14:15]
	global_load_lds_dwordx4 v[224:225], off
	s_add_i32 m0, s64, 0x2000
	v_lshl_add_u64 v[228:229], s[42:43], 0, v[136:137]
	global_load_lds_dwordx4 v[226:227], off
	s_mov_b32 m0, s47
	v_lshl_add_u64 v[244:245], s[42:43], 0, v[134:135]
	global_load_lds_dwordx4 v[228:229], off
	s_mov_b32 m0, s48
	s_nop 0
	global_load_lds_dwordx4 v[244:245], off
	s_setprio 1
	s_waitcnt vmcnt(8) lgkmcnt(0)
	s_barrier
; #define PG8_STAGE(bufoff, gbase, voff) do { _Pragma("unroll") for (int _i = 0; _i < 2; ++_i) \
;         __builtin_amdgcn_global_load_lds((const unsigned*)((const char*)(gbase) + (voff)[_i]), (LAS unsigned*)(lds + (bufoff) + ldsw + _i * 8192), 16, 0, 0); } while (0)
; #define PG8_LDA(dst, b, h) do { _Pragma("unroll") for (int m = 0; m < 4; ++m) _Pragma("unroll") for (int k = 0; k < 2; ++k) dst[m][k] = *(const LAS bf16x8*)(lds + PG8_SA(b, h) + aoff + m * 2048 + k * 1024); } while (0)
; #define PG8_LDB(dst, b, h) do { _Pragma("unroll") for (int n = 0; n < 2; ++n) _Pragma("unroll") for (int k = 0; k < 2; ++k) dst[n][k] = *(const LAS bf16x8*)(lds + PG8_SB(b, h) + boff + n * 2048 + k * 1024); } while (0)
; #define PG8_MMA(ai, bj, At, Bt) do { __builtin_amdgcn_s_setprio(1); _Pragma("unroll") for (int m = 0; m < 4; ++m) _Pragma("unroll") for (int n = 0; n < 2; ++n) _Pragma("unroll") for (int k = 0; k < 2; ++k) \
;         acc[ai][bj][m][n] = __builtin_amdgcn_mfma_f32_16x16x32_bf16(Bt[n][k], At[m][k], acc[ai][bj][m][n], 0, 0, 0); __builtin_amdgcn_s_setprio(0); } while (0)
; #define PG8_WAIT_V(n) asm volatile("s_waitcnt vmcnt(" #n ")" ::: "memory")
; #define PG8_BAR __builtin_amdgcn_s_barrier()
; template <class Epi, bool SEG>
; __device__ __forceinline__ void gemm_phase(LAS unsigned char* lds, const Gemm g, const int G, const int cidx, const Epi& E) {
;     ...
;             PG8_LDB(B0, 0, 0); PG8_LDB(B1, 0, 1); PG8_SCHED; PG8_LDA(At, 0, 0); PG8_STAGE(PG8_SA(1, 1), a1 + hstepA, voffA);
;             PG8_WAIT_V(8); PG8_WAIT_L(0); PG8_BAR; PG8_MMA(0, 0, At, B0); PG8_MMA(0, 1, At, B1); PG8_BAR; PG8_SCHED;
;             PG8_LDA(At, 0, 1); PG8_STAGE(PG8_SB(0, 0), b2, voffB); PG8_STAGE(PG8_SB(0, 1), b2 + hstepB, voffB); PG8_STAGE(PG8_SA(0, 0), a2, voffA);
;             PG8_WAIT_V(8); PG8_WAIT_L(0); PG8_BAR; PG8_MMA(1, 0, At, B0); PG8_MMA(1, 1, At, B1); PG8_BAR; PG8_SCHED;
;             PG8_LDB(B0, 1, 0); PG8_LDB(B1, 1, 1); PG8_SCHED; PG8_LDA(At, 1, 0); PG8_STAGE(PG8_SA(0, 1), a2 + hstepA, voffA);
;             PG8_WAIT_V(8); PG8_WAIT_L(0); PG8_BAR; PG8_MMA(0, 0, At, B0); PG8_MMA(0, 1, At, B1); PG8_BAR; PG8_SCHED;
;             PG8_LDA(At, 1, 1); PG8_STAGE(PG8_SB(1, 0), b3, voffB); PG8_STAGE(PG8_SB(1, 1), b3 + hstepB, voffB); PG8_STAGE(PG8_SA(1, 0), a3, voffA);
;             PG8_WAIT_V(8); PG8_WAIT_L(0); PG8_BAR; PG8_MMA(1, 0, At, B0); PG8_MMA(1, 1, At, B1); PG8_BAR; PG8_SCHED;
	v_mfma_f32_16x16x32_bf16 v[66:69], v[146:149], v[178:181], v[66:69]
	v_mfma_f32_16x16x32_bf16 v[62:65], v[154:157], v[178:181], v[62:65]
	v_mfma_f32_16x16x32_bf16 v[58:61], v[146:149], v[186:189], v[58:61]
	v_mfma_f32_16x16x32_bf16 v[54:57], v[154:157], v[186:189], v[54:57]
	v_mfma_f32_16x16x32_bf16 v[42:45], v[146:149], v[194:197], v[42:45]
	v_mfma_f32_16x16x32_bf16 v[38:41], v[154:157], v[194:197], v[38:41]
	v_mfma_f32_16x16x32_bf16 v[26:29], v[146:149], v[212:215], v[26:29]
	v_mfma_f32_16x16x32_bf16 v[22:25], v[154:157], v[212:215], v[22:25]
	v_mfma_f32_16x16x32_bf16 v[66:69], v[150:153], v[182:185], v[66:69]
	v_mfma_f32_16x16x32_bf16 v[62:65], v[158:161], v[182:185], v[62:65]
	v_mfma_f32_16x16x32_bf16 v[58:61], v[150:153], v[190:193], v[58:61]
	v_mfma_f32_16x16x32_bf16 v[54:57], v[158:161], v[190:193], v[54:57]
	v_mfma_f32_16x16x32_bf16 v[42:45], v[150:153], v[198:201], v[42:45]
	v_mfma_f32_16x16x32_bf16 v[38:41], v[158:161], v[198:201], v[38:41]
	v_mfma_f32_16x16x32_bf16 v[26:29], v[150:153], v[216:219], v[26:29]
	v_mfma_f32_16x16x32_bf16 v[22:25], v[158:161], v[216:219], v[22:25]
	s_setprio 0
	s_setprio 1
	v_mfma_f32_16x16x32_bf16 v[50:53], v[162:165], v[178:181], v[50:53]
	v_mfma_f32_16x16x32_bf16 v[46:49], v[170:173], v[178:181], v[46:49]
	v_mfma_f32_16x16x32_bf16 v[34:37], v[162:165], v[186:189], v[34:37]
	v_mfma_f32_16x16x32_bf16 v[30:33], v[170:173], v[186:189], v[30:33]
	v_mfma_f32_16x16x32_bf16 v[18:21], v[162:165], v[194:197], v[18:21]
	v_mfma_f32_16x16x32_bf16 v[10:13], v[170:173], v[194:197], v[10:13]
	v_mfma_f32_16x16x32_bf16 v[6:9], v[162:165], v[212:215], v[6:9]
	v_mfma_f32_16x16x32_bf16 v[2:5], v[170:173], v[212:215], v[2:5]
	v_mfma_f32_16x16x32_bf16 v[50:53], v[166:169], v[182:185], v[50:53]
	v_mfma_f32_16x16x32_bf16 v[46:49], v[174:177], v[182:185], v[46:49]
	v_mfma_f32_16x16x32_bf16 v[34:37], v[166:169], v[190:193], v[34:37]
	v_mfma_f32_16x16x32_bf16 v[30:33], v[174:177], v[190:193], v[30:33]
	v_mfma_f32_16x16x32_bf16 v[18:21], v[166:169], v[198:201], v[18:21]
	v_mfma_f32_16x16x32_bf16 v[10:13], v[174:177], v[198:201], v[10:13]
	v_mfma_f32_16x16x32_bf16 v[6:9], v[166:169], v[216:219], v[6:9]
	s_setprio 0
	v_mfma_f32_16x16x32_bf16 v[2:5], v[174:177], v[216:219], v[2:5]
	s_barrier
	s_add_i32 s64, 0, 0x18000
	v_add_u32_e32 v145, s64, v142
	s_add_i32 s65, 0, 0x1c000
	ds_read_b128 v[146:149], v145
	ds_read_b128 v[150:153], v145 offset:1024
	ds_read_b128 v[154:157], v145 offset:2048
	ds_read_b128 v[158:161], v145 offset:3072
	v_add_u32_e32 v145, s65, v142
	ds_read_b128 v[162:165], v145
	ds_read_b128 v[166:169], v145 offset:1024
	ds_read_b128 v[170:173], v145 offset:2048
	ds_read_b128 v[174:177], v145 offset:3072
	s_add_u32 s22, s42, 0x30000
	s_addc_u32 s23, s43, 0
	s_mov_b32 m0, s49
	v_lshl_add_u64 v[246:247], s[22:23], 0, v[136:137]
	ds_read_b128 v[178:181], v144 offset:32768
	ds_read_b128 v[182:185], v144 offset:33792
	ds_read_b128 v[186:189], v144 offset:34816
	ds_read_b128 v[190:193], v144 offset:35840
	ds_read_b128 v[194:197], v144 offset:36864
	ds_read_b128 v[198:201], v144 offset:37888
	ds_read_b128 v[212:215], v144 offset:38912
	ds_read_b128 v[216:219], v144 offset:39936
	global_load_lds_dwordx4 v[246:247], off
	v_lshl_add_u64 v[246:247], s[22:23], 0, v[134:135]
	s_mov_b32 m0, s50
	s_nop 0
	global_load_lds_dwordx4 v[246:247], off
	s_setprio 1
	s_waitcnt vmcnt(8) lgkmcnt(0)
	s_barrier
	v_mfma_f32_16x16x32_bf16 v[130:133], v[146:149], v[178:181], v[130:133]
	v_mfma_f32_16x16x32_bf16 v[126:129], v[154:157], v[178:181], v[126:129]
	v_mfma_f32_16x16x32_bf16 v[122:125], v[146:149], v[186:189], v[122:125]
	v_mfma_f32_16x16x32_bf16 v[118:121], v[154:157], v[186:189], v[118:121]
	v_mfma_f32_16x16x32_bf16 v[106:109], v[146:149], v[194:197], v[106:109]
	v_mfma_f32_16x16x32_bf16 v[102:105], v[154:157], v[194:197], v[102:105]
	v_mfma_f32_16x16x32_bf16 v[90:93], v[146:149], v[212:215], v[90:93]
	v_mfma_f32_16x16x32_bf16 v[86:89], v[154:157], v[212:215], v[86:89]
	v_mfma_f32_16x16x32_bf16 v[130:133], v[150:153], v[182:185], v[130:133]
	v_mfma_f32_16x16x32_bf16 v[126:129], v[158:161], v[182:185], v[126:129]
	v_mfma_f32_16x16x32_bf16 v[122:125], v[150:153], v[190:193], v[122:125]
	v_mfma_f32_16x16x32_bf16 v[118:121], v[158:161], v[190:193], v[118:121]
	v_mfma_f32_16x16x32_bf16 v[106:109], v[150:153], v[198:201], v[106:109]
	v_mfma_f32_16x16x32_bf16 v[102:105], v[158:161], v[198:201], v[102:105]
	v_mfma_f32_16x16x32_bf16 v[90:93], v[150:153], v[216:219], v[90:93]
	v_mfma_f32_16x16x32_bf16 v[86:89], v[158:161], v[216:219], v[86:89]
	s_setprio 0
	s_setprio 1
	v_mfma_f32_16x16x32_bf16 v[114:117], v[162:165], v[178:181], v[114:117]
	v_mfma_f32_16x16x32_bf16 v[110:113], v[170:173], v[178:181], v[110:113]
	v_mfma_f32_16x16x32_bf16 v[98:101], v[162:165], v[186:189], v[98:101]
	v_mfma_f32_16x16x32_bf16 v[94:97], v[170:173], v[186:189], v[94:97]
	v_mfma_f32_16x16x32_bf16 v[82:85], v[162:165], v[194:197], v[82:85]
	v_mfma_f32_16x16x32_bf16 v[78:81], v[170:173], v[194:197], v[78:81]
	v_mfma_f32_16x16x32_bf16 v[74:77], v[162:165], v[212:215], v[74:77]
	v_mfma_f32_16x16x32_bf16 v[70:73], v[170:173], v[212:215], v[70:73]
	v_mfma_f32_16x16x32_bf16 v[114:117], v[166:169], v[182:185], v[114:117]
	v_mfma_f32_16x16x32_bf16 v[110:113], v[174:177], v[182:185], v[110:113]
	v_mfma_f32_16x16x32_bf16 v[98:101], v[166:169], v[190:193], v[98:101]
	v_mfma_f32_16x16x32_bf16 v[94:97], v[174:177], v[190:193], v[94:97]
	v_mfma_f32_16x16x32_bf16 v[82:85], v[166:169], v[198:201], v[82:85]
	v_mfma_f32_16x16x32_bf16 v[78:81], v[174:177], v[198:201], v[78:81]
	v_mfma_f32_16x16x32_bf16 v[74:77], v[166:169], v[216:219], v[74:77]
	s_setprio 0
	v_mfma_f32_16x16x32_bf16 v[70:73], v[174:177], v[216:219], v[70:73]
	s_barrier
; #define PG8_STAGE(bufoff, gbase, voff) do { _Pragma("unroll") for (int _i = 0; _i < 2; ++_i) \
;         __builtin_amdgcn_global_load_lds((const unsigned*)((const char*)(gbase) + (voff)[_i]), (LAS unsigned*)(lds + (bufoff) + ldsw + _i * 8192), 16, 0, 0); } while (0)
; #define PG8_LDA(dst, b, h) do { _Pragma("unroll") for (int m = 0; m < 4; ++m) _Pragma("unroll") for (int k = 0; k < 2; ++k) dst[m][k] = *(const LAS bf16x8*)(lds + PG8_SA(b, h) + aoff + m * 2048 + k * 1024); } while (0)
; #define PG8_LDB(dst, b, h) do { _Pragma("unroll") for (int n = 0; n < 2; ++n) _Pragma("unroll") for (int k = 0; k < 2; ++k) dst[n][k] = *(const LAS bf16x8*)(lds + PG8_SB(b, h) + boff + n * 2048 + k * 1024); } while (0)
; #define PG8_MMA(ai, bj, At, Bt) do { __builtin_amdgcn_s_setprio(1); _Pragma("unroll") for (int m = 0; m < 4; ++m) _Pragma("unroll") for (int n = 0; n < 2; ++n) _Pragma("unroll") for (int k = 0; k < 2; ++k) \
;         acc[ai][bj][m][n] = __builtin_amdgcn_mfma_f32_16x16x32_bf16(Bt[n][k], At[m][k], acc[ai][bj][m][n], 0, 0, 0); __builtin_amdgcn_s_setprio(0); } while (0)
; #define PG8_WAIT_V(n) asm volatile("s_waitcnt vmcnt(" #n ")" ::: "memory")
; #define PG8_BAR __builtin_amdgcn_s_barrier()
; template <class Epi, bool SEG>
; __device__ __forceinline__ void gemm_phase(LAS unsigned char* lds, const Gemm g, const int G, const int cidx, const Epi& E) {
;     ...
;             PG8_LDB(B0, 0, 0); PG8_LDB(B1, 0, 1); PG8_SCHED; PG8_LDA(At, 0, 0); PG8_STAGE(PG8_SA(1, 1), a1 + hstepA, voffA);
;             PG8_WAIT_V(8); PG8_WAIT_L(0); PG8_BAR; PG8_MMA(0, 0, At, B0); PG8_MMA(0, 1, At, B1); PG8_BAR; PG8_SCHED;
;             PG8_LDA(At, 0, 1); PG8_STAGE(PG8_SB(0, 0), b2, voffB); PG8_STAGE(PG8_SB(0, 1), b2 + hstepB, voffB); PG8_STAGE(PG8_SA(0, 0), a2, voffA);
;             PG8_WAIT_V(8); PG8_WAIT_L(0); PG8_BAR; PG8_MMA(1, 0, At, B0); PG8_MMA(1, 1, At, B1); PG8_BAR; PG8_SCHED;
;             PG8_LDB(B0, 1, 0); PG8_LDB(B1, 1, 1); PG8_SCHED; PG8_LDA(At, 1, 0); PG8_STAGE(PG8_SA(0, 1), a2 + hstepA, voffA);
;             PG8_WAIT_V(8); PG8_WAIT_L(0); PG8_BAR; PG8_MMA(0, 0, At, B0); PG8_MMA(0, 1, At, B1); PG8_BAR; PG8_SCHED;
;             PG8_LDA(At, 1, 1); PG8_STAGE(PG8_SB(1, 0), b3, voffB); PG8_STAGE(PG8_SB(1, 1), b3 + hstepB, voffB); PG8_STAGE(PG8_SA(1, 0), a3, voffA);
;             PG8_WAIT_V(8); PG8_WAIT_L(0); PG8_BAR; PG8_MMA(1, 0, At, B0); PG8_MMA(1, 1, At, B1); PG8_BAR; PG8_SCHED;
	s_add_i32 s22, s64, s39
	v_lshl_add_u64 v[220:221], v[220:221], 0, s[28:29]
	s_mov_b32 m0, s22
	ds_read_b128 v[178:181], v144 offset:49152
	ds_read_b128 v[182:185], v144 offset:50176
	ds_read_b128 v[186:189], v144 offset:51200
	ds_read_b128 v[190:193], v144 offset:52224
	ds_read_b128 v[194:197], v144 offset:53248
	ds_read_b128 v[198:201], v144 offset:54272
	ds_read_b128 v[212:215], v144 offset:55296
	ds_read_b128 v[216:219], v144 offset:56320
	global_load_lds_dwordx4 v[220:221], off
	v_lshl_add_u64 v[220:221], v[222:223], 0, s[28:29]
	s_add_i32 m0, s22, 0x2000
	s_add_i32 s22, s65, s39
	global_load_lds_dwordx4 v[220:221], off
	v_lshl_add_u64 v[220:221], v[224:225], 0, s[28:29]
	s_mov_b32 m0, s22
	s_nop 0
	global_load_lds_dwordx4 v[220:221], off
	v_lshl_add_u64 v[220:221], v[226:227], 0, s[28:29]
	s_add_i32 m0, s22, 0x2000
	s_nop 0
	global_load_lds_dwordx4 v[220:221], off
	v_lshl_add_u64 v[220:221], v[228:229], 0, s[28:29]
	s_mov_b32 m0, s55
	s_nop 0
	global_load_lds_dwordx4 v[220:221], off
	v_lshl_add_u64 v[220:221], v[244:245], 0, s[28:29]
	s_mov_b32 m0, s56
	s_nop 0
	global_load_lds_dwordx4 v[220:221], off
	s_setprio 1
	s_waitcnt vmcnt(8) lgkmcnt(0)
	s_barrier
	v_mfma_f32_16x16x32_bf16 v[66:69], v[146:149], v[178:181], v[66:69]
	v_mfma_f32_16x16x32_bf16 v[62:65], v[154:157], v[178:181], v[62:65]
	v_mfma_f32_16x16x32_bf16 v[58:61], v[146:149], v[186:189], v[58:61]
	v_mfma_f32_16x16x32_bf16 v[54:57], v[154:157], v[186:189], v[54:57]
	v_mfma_f32_16x16x32_bf16 v[42:45], v[146:149], v[194:197], v[42:45]
	v_mfma_f32_16x16x32_bf16 v[38:41], v[154:157], v[194:197], v[38:41]
	v_mfma_f32_16x16x32_bf16 v[26:29], v[146:149], v[212:215], v[26:29]
	v_mfma_f32_16x16x32_bf16 v[22:25], v[154:157], v[212:215], v[22:25]
	v_mfma_f32_16x16x32_bf16 v[66:69], v[150:153], v[182:185], v[66:69]
	v_mfma_f32_16x16x32_bf16 v[62:65], v[158:161], v[182:185], v[62:65]
	v_mfma_f32_16x16x32_bf16 v[58:61], v[150:153], v[190:193], v[58:61]
	v_mfma_f32_16x16x32_bf16 v[54:57], v[158:161], v[190:193], v[54:57]
	v_mfma_f32_16x16x32_bf16 v[42:45], v[150:153], v[198:201], v[42:45]
	v_mfma_f32_16x16x32_bf16 v[38:41], v[158:161], v[198:201], v[38:41]
	v_mfma_f32_16x16x32_bf16 v[26:29], v[150:153], v[216:219], v[26:29]
	v_mfma_f32_16x16x32_bf16 v[22:25], v[158:161], v[216:219], v[22:25]
	s_setprio 0
	s_setprio 1
	v_mfma_f32_16x16x32_bf16 v[50:53], v[162:165], v[178:181], v[50:53]
	v_mfma_f32_16x16x32_bf16 v[46:49], v[170:173], v[178:181], v[46:49]
	v_mfma_f32_16x16x32_bf16 v[34:37], v[162:165], v[186:189], v[34:37]
	v_mfma_f32_16x16x32_bf16 v[30:33], v[170:173], v[186:189], v[30:33]
	v_mfma_f32_16x16x32_bf16 v[18:21], v[162:165], v[194:197], v[18:21]
	v_mfma_f32_16x16x32_bf16 v[10:13], v[170:173], v[194:197], v[10:13]
	v_mfma_f32_16x16x32_bf16 v[6:9], v[162:165], v[212:215], v[6:9]
	v_mfma_f32_16x16x32_bf16 v[2:5], v[170:173], v[212:215], v[2:5]
	v_mfma_f32_16x16x32_bf16 v[50:53], v[166:169], v[182:185], v[50:53]
	v_mfma_f32_16x16x32_bf16 v[46:49], v[174:177], v[182:185], v[46:49]
	v_mfma_f32_16x16x32_bf16 v[34:37], v[166:169], v[190:193], v[34:37]
	v_mfma_f32_16x16x32_bf16 v[30:33], v[174:177], v[190:193], v[30:33]
	v_mfma_f32_16x16x32_bf16 v[18:21], v[166:169], v[198:201], v[18:21]
	v_mfma_f32_16x16x32_bf16 v[10:13], v[174:177], v[198:201], v[10:13]
	v_mfma_f32_16x16x32_bf16 v[6:9], v[166:169], v[216:219], v[6:9]
	s_setprio 0
	v_mfma_f32_16x16x32_bf16 v[2:5], v[174:177], v[216:219], v[2:5]
	s_barrier
	s_add_u32 s61, s61, 0x100
	s_addc_u32 s62, s62, 0
	s_cmp_ge_u32 s63, s53
	s_mov_b64 s[22:23], s[40:41]
	s_mov_b32 s42, s63
	s_cbranch_scc0 .LBB0_1060
	s_and_b64 vcc, exec, s[16:17]
	s_cbranch_vccz .LBB0_1063
	s_barrier
